# gates epilogue packed fma clamp + attention step loop trims (persistent -mrun SrcC quads, immediate offsets for V tr-reads)
# speedup vs baseline: 1.0068x; 1.0019x over previous
.LBB0_345:
	s_and_b64 vcc, exec, s[8:9]
	s_cbranch_vccz .LBB0_366
	s_lshl_b32 s9, s87, 2
	s_add_i32 s0, s87, -16
	s_lshl_b32 s8, s88, 4
	s_and_b32 s9, s9, 12
	s_or_b32 s8, s9, s8
	s_lshr_b32 s0, s0, 2
	s_add_i32 s8, s8, s0
	s_ashr_i32 s9, s8, 31
	s_lshl_b64 s[8:9], s[8:9], 16
	v_lshl_add_u64 v[0:1], v[190:191], 0, s[8:9]
	s_mov_b64 s[8:9], 0x1000
	v_lshl_add_u64 v[26:27], v[0:1], 0, s[8:9]
	v_mov_b32_e32 v28, 0xbfb8aa3b
	v_mov_b32_e32 v29, 0xbfb8aa3b
	v_pk_mul_f32 v[2:3], v[162:163], v[28:29]
	v_pk_mul_f32 v[4:5], v[164:165], v[28:29]
	v_pk_mul_f32 v[6:7], v[158:159], v[28:29]
	v_pk_mul_f32 v[8:9], v[160:161], v[28:29]
	v_pk_mul_f32 v[10:11], v[154:155], v[28:29]
	v_pk_mul_f32 v[12:13], v[156:157], v[28:29]
	v_pk_mul_f32 v[14:15], v[150:151], v[28:29]
	v_pk_mul_f32 v[16:17], v[152:153], v[28:29]
	v_exp_f32_e32 v2, v2
	v_exp_f32_e32 v3, v3
	v_exp_f32_e32 v4, v4
	v_exp_f32_e32 v5, v5
	v_exp_f32_e32 v6, v6
	v_exp_f32_e32 v7, v7
	v_exp_f32_e32 v8, v8
	v_exp_f32_e32 v9, v9
	v_exp_f32_e32 v10, v10
	v_exp_f32_e32 v11, v11
	v_exp_f32_e32 v12, v12
	v_exp_f32_e32 v13, v13
	v_exp_f32_e32 v14, v14
	v_exp_f32_e32 v15, v15
	v_exp_f32_e32 v16, v16
	v_exp_f32_e32 v17, v17
	v_pk_fma_f32 v[2:3], v[2:3], v[216:217], v[216:217] op_sel:[0,1,1] op_sel_hi:[1,1,1] clamp
	v_pk_fma_f32 v[4:5], v[4:5], v[216:217], v[216:217] op_sel:[0,1,1] op_sel_hi:[1,1,1] clamp
	v_pk_fma_f32 v[6:7], v[6:7], v[216:217], v[216:217] op_sel:[0,1,1] op_sel_hi:[1,1,1] clamp
	v_pk_fma_f32 v[8:9], v[8:9], v[216:217], v[216:217] op_sel:[0,1,1] op_sel_hi:[1,1,1] clamp
	v_pk_fma_f32 v[10:11], v[10:11], v[216:217], v[216:217] op_sel:[0,1,1] op_sel_hi:[1,1,1] clamp
	v_pk_fma_f32 v[12:13], v[12:13], v[216:217], v[216:217] op_sel:[0,1,1] op_sel_hi:[1,1,1] clamp
	v_pk_fma_f32 v[14:15], v[14:15], v[216:217], v[216:217] op_sel:[0,1,1] op_sel_hi:[1,1,1] clamp
	v_pk_fma_f32 v[16:17], v[16:17], v[216:217], v[216:217] op_sel:[0,1,1] op_sel_hi:[1,1,1] clamp
	v_rcp_f32_e32 v2, v2
	v_rcp_f32_e32 v3, v3
	v_rcp_f32_e32 v4, v4
	v_rcp_f32_e32 v5, v5
	v_rcp_f32_e32 v6, v6
	v_rcp_f32_e32 v7, v7
	v_rcp_f32_e32 v8, v8
	v_rcp_f32_e32 v9, v9
	v_rcp_f32_e32 v10, v10
	v_rcp_f32_e32 v11, v11
	v_rcp_f32_e32 v12, v12
	v_rcp_f32_e32 v13, v13
	v_rcp_f32_e32 v14, v14
	v_rcp_f32_e32 v15, v15
	v_rcp_f32_e32 v16, v16
	v_rcp_f32_e32 v17, v17
	v_cvt_pk_u8_f32 v18, v2, 0, 0
	v_cvt_pk_u8_f32 v19, v6, 0, 0
	v_cvt_pk_u8_f32 v20, v10, 0, 0
	v_cvt_pk_u8_f32 v21, v14, 0, 0
	v_cvt_pk_u8_f32 v18, v3, 1, v18
	v_cvt_pk_u8_f32 v19, v7, 1, v19
	v_cvt_pk_u8_f32 v20, v11, 1, v20
	v_cvt_pk_u8_f32 v21, v15, 1, v21
	v_cvt_pk_u8_f32 v18, v4, 2, v18
	v_cvt_pk_u8_f32 v19, v8, 2, v19
	v_cvt_pk_u8_f32 v20, v12, 2, v20
	v_cvt_pk_u8_f32 v21, v16, 2, v21
	v_cvt_pk_u8_f32 v18, v5, 3, v18
	v_cvt_pk_u8_f32 v19, v9, 3, v19
	v_cvt_pk_u8_f32 v20, v13, 3, v20
	v_cvt_pk_u8_f32 v21, v17, 3, v21
	global_store_dwordx4 v[0:1], v[18:21], off nt
	v_pk_mul_f32 v[2:3], v[146:147], v[28:29]
	v_pk_mul_f32 v[4:5], v[148:149], v[28:29]
	v_pk_mul_f32 v[6:7], v[142:143], v[28:29]
	v_pk_mul_f32 v[8:9], v[144:145], v[28:29]
	v_pk_mul_f32 v[10:11], v[138:139], v[28:29]
	v_pk_mul_f32 v[12:13], v[140:141], v[28:29]
	v_pk_mul_f32 v[14:15], v[134:135], v[28:29]
	v_pk_mul_f32 v[16:17], v[136:137], v[28:29]
	v_exp_f32_e32 v2, v2
	v_exp_f32_e32 v3, v3
	v_exp_f32_e32 v4, v4
	v_exp_f32_e32 v5, v5
	v_exp_f32_e32 v6, v6
	v_exp_f32_e32 v7, v7
	v_exp_f32_e32 v8, v8
	v_exp_f32_e32 v9, v9
	v_exp_f32_e32 v10, v10
	v_exp_f32_e32 v11, v11
	v_exp_f32_e32 v12, v12
	v_exp_f32_e32 v13, v13
	v_exp_f32_e32 v14, v14
	v_exp_f32_e32 v15, v15
	v_exp_f32_e32 v16, v16
	v_exp_f32_e32 v17, v17
	v_pk_fma_f32 v[2:3], v[2:3], v[216:217], v[216:217] op_sel:[0,1,1] op_sel_hi:[1,1,1] clamp
	v_pk_fma_f32 v[4:5], v[4:5], v[216:217], v[216:217] op_sel:[0,1,1] op_sel_hi:[1,1,1] clamp
	v_pk_fma_f32 v[6:7], v[6:7], v[216:217], v[216:217] op_sel:[0,1,1] op_sel_hi:[1,1,1] clamp
	v_pk_fma_f32 v[8:9], v[8:9], v[216:217], v[216:217] op_sel:[0,1,1] op_sel_hi:[1,1,1] clamp
	v_pk_fma_f32 v[10:11], v[10:11], v[216:217], v[216:217] op_sel:[0,1,1] op_sel_hi:[1,1,1] clamp
	v_pk_fma_f32 v[12:13], v[12:13], v[216:217], v[216:217] op_sel:[0,1,1] op_sel_hi:[1,1,1] clamp
	v_pk_fma_f32 v[14:15], v[14:15], v[216:217], v[216:217] op_sel:[0,1,1] op_sel_hi:[1,1,1] clamp
	v_pk_fma_f32 v[16:17], v[16:17], v[216:217], v[216:217] op_sel:[0,1,1] op_sel_hi:[1,1,1] clamp
	v_rcp_f32_e32 v2, v2
	v_rcp_f32_e32 v3, v3
	v_rcp_f32_e32 v4, v4
	v_rcp_f32_e32 v5, v5
	v_rcp_f32_e32 v6, v6
	v_rcp_f32_e32 v7, v7
	v_rcp_f32_e32 v8, v8
	v_rcp_f32_e32 v9, v9
	v_rcp_f32_e32 v10, v10
	v_rcp_f32_e32 v11, v11
	v_rcp_f32_e32 v12, v12
	v_rcp_f32_e32 v13, v13
	v_rcp_f32_e32 v14, v14
	v_rcp_f32_e32 v15, v15
	v_rcp_f32_e32 v16, v16
	v_rcp_f32_e32 v17, v17
	v_cvt_pk_u8_f32 v22, v2, 0, 0
	v_cvt_pk_u8_f32 v23, v6, 0, 0
	v_cvt_pk_u8_f32 v24, v10, 0, 0
	v_cvt_pk_u8_f32 v25, v14, 0, 0
	v_cvt_pk_u8_f32 v22, v3, 1, v22
	v_cvt_pk_u8_f32 v23, v7, 1, v23
	v_cvt_pk_u8_f32 v24, v11, 1, v24
	v_cvt_pk_u8_f32 v25, v15, 1, v25
	v_cvt_pk_u8_f32 v22, v4, 2, v22
	v_cvt_pk_u8_f32 v23, v8, 2, v23
	v_cvt_pk_u8_f32 v24, v12, 2, v24
	v_cvt_pk_u8_f32 v25, v16, 2, v25
	v_cvt_pk_u8_f32 v22, v5, 3, v22
	v_cvt_pk_u8_f32 v23, v9, 3, v23
	v_cvt_pk_u8_f32 v24, v13, 3, v24
	v_cvt_pk_u8_f32 v25, v17, 3, v25
	global_store_dwordx4 v[0:1], v[22:25], off offset:1024 nt
	v_pk_mul_f32 v[2:3], v[130:131], v[28:29]
	v_pk_mul_f32 v[4:5], v[132:133], v[28:29]
	v_pk_mul_f32 v[6:7], v[126:127], v[28:29]
	v_pk_mul_f32 v[8:9], v[128:129], v[28:29]
	v_pk_mul_f32 v[10:11], v[122:123], v[28:29]
	v_pk_mul_f32 v[12:13], v[124:125], v[28:29]
	v_pk_mul_f32 v[14:15], v[118:119], v[28:29]
	v_pk_mul_f32 v[16:17], v[120:121], v[28:29]
	v_exp_f32_e32 v2, v2
	v_exp_f32_e32 v3, v3
	v_exp_f32_e32 v4, v4
	v_exp_f32_e32 v5, v5
	v_exp_f32_e32 v6, v6
	v_exp_f32_e32 v7, v7
	v_exp_f32_e32 v8, v8
	v_exp_f32_e32 v9, v9
	v_exp_f32_e32 v10, v10
	v_exp_f32_e32 v11, v11
	v_exp_f32_e32 v12, v12
	v_exp_f32_e32 v13, v13
	v_exp_f32_e32 v14, v14
	v_exp_f32_e32 v15, v15
	v_exp_f32_e32 v16, v16
	v_exp_f32_e32 v17, v17
	v_pk_fma_f32 v[2:3], v[2:3], v[216:217], v[216:217] op_sel:[0,1,1] op_sel_hi:[1,1,1] clamp
	v_pk_fma_f32 v[4:5], v[4:5], v[216:217], v[216:217] op_sel:[0,1,1] op_sel_hi:[1,1,1] clamp
	v_pk_fma_f32 v[6:7], v[6:7], v[216:217], v[216:217] op_sel:[0,1,1] op_sel_hi:[1,1,1] clamp
	v_pk_fma_f32 v[8:9], v[8:9], v[216:217], v[216:217] op_sel:[0,1,1] op_sel_hi:[1,1,1] clamp
	v_pk_fma_f32 v[10:11], v[10:11], v[216:217], v[216:217] op_sel:[0,1,1] op_sel_hi:[1,1,1] clamp
	v_pk_fma_f32 v[12:13], v[12:13], v[216:217], v[216:217] op_sel:[0,1,1] op_sel_hi:[1,1,1] clamp
	v_pk_fma_f32 v[14:15], v[14:15], v[216:217], v[216:217] op_sel:[0,1,1] op_sel_hi:[1,1,1] clamp
	v_pk_fma_f32 v[16:17], v[16:17], v[216:217], v[216:217] op_sel:[0,1,1] op_sel_hi:[1,1,1] clamp
	v_rcp_f32_e32 v2, v2
	v_rcp_f32_e32 v3, v3
	v_rcp_f32_e32 v4, v4
	v_rcp_f32_e32 v5, v5
	v_rcp_f32_e32 v6, v6
	v_rcp_f32_e32 v7, v7
	v_rcp_f32_e32 v8, v8
	v_rcp_f32_e32 v9, v9
	v_rcp_f32_e32 v10, v10
	v_rcp_f32_e32 v11, v11
	v_rcp_f32_e32 v12, v12
	v_rcp_f32_e32 v13, v13
	v_rcp_f32_e32 v14, v14
	v_rcp_f32_e32 v15, v15
	v_rcp_f32_e32 v16, v16
	v_rcp_f32_e32 v17, v17
	v_cvt_pk_u8_f32 v18, v2, 0, 0
	v_cvt_pk_u8_f32 v19, v6, 0, 0
	v_cvt_pk_u8_f32 v20, v10, 0, 0
	v_cvt_pk_u8_f32 v21, v14, 0, 0
	v_cvt_pk_u8_f32 v18, v3, 1, v18
	v_cvt_pk_u8_f32 v19, v7, 1, v19
	v_cvt_pk_u8_f32 v20, v11, 1, v20
	v_cvt_pk_u8_f32 v21, v15, 1, v21
	v_cvt_pk_u8_f32 v18, v4, 2, v18
	v_cvt_pk_u8_f32 v19, v8, 2, v19
	v_cvt_pk_u8_f32 v20, v12, 2, v20
	v_cvt_pk_u8_f32 v21, v16, 2, v21
	v_cvt_pk_u8_f32 v18, v5, 3, v18
	v_cvt_pk_u8_f32 v19, v9, 3, v19
	v_cvt_pk_u8_f32 v20, v13, 3, v20
	v_cvt_pk_u8_f32 v21, v17, 3, v21
	global_store_dwordx4 v[0:1], v[18:21], off offset:2048 nt
	v_pk_mul_f32 v[2:3], v[114:115], v[28:29]
	v_pk_mul_f32 v[4:5], v[116:117], v[28:29]
	v_pk_mul_f32 v[6:7], v[110:111], v[28:29]
	v_pk_mul_f32 v[8:9], v[112:113], v[28:29]
	v_pk_mul_f32 v[10:11], v[106:107], v[28:29]
	v_pk_mul_f32 v[12:13], v[108:109], v[28:29]
	v_pk_mul_f32 v[14:15], v[102:103], v[28:29]
	v_pk_mul_f32 v[16:17], v[104:105], v[28:29]
	v_exp_f32_e32 v2, v2
	v_exp_f32_e32 v3, v3
	v_exp_f32_e32 v4, v4
	v_exp_f32_e32 v5, v5
	v_exp_f32_e32 v6, v6
	v_exp_f32_e32 v7, v7
	v_exp_f32_e32 v8, v8
	v_exp_f32_e32 v9, v9
	v_exp_f32_e32 v10, v10
	v_exp_f32_e32 v11, v11
	v_exp_f32_e32 v12, v12
	v_exp_f32_e32 v13, v13
	v_exp_f32_e32 v14, v14
	v_exp_f32_e32 v15, v15
	v_exp_f32_e32 v16, v16
	v_exp_f32_e32 v17, v17
	v_pk_fma_f32 v[2:3], v[2:3], v[216:217], v[216:217] op_sel:[0,1,1] op_sel_hi:[1,1,1] clamp
	v_pk_fma_f32 v[4:5], v[4:5], v[216:217], v[216:217] op_sel:[0,1,1] op_sel_hi:[1,1,1] clamp
	v_pk_fma_f32 v[6:7], v[6:7], v[216:217], v[216:217] op_sel:[0,1,1] op_sel_hi:[1,1,1] clamp
	v_pk_fma_f32 v[8:9], v[8:9], v[216:217], v[216:217] op_sel:[0,1,1] op_sel_hi:[1,1,1] clamp
	v_pk_fma_f32 v[10:11], v[10:11], v[216:217], v[216:217] op_sel:[0,1,1] op_sel_hi:[1,1,1] clamp
	v_pk_fma_f32 v[12:13], v[12:13], v[216:217], v[216:217] op_sel:[0,1,1] op_sel_hi:[1,1,1] clamp
	v_pk_fma_f32 v[14:15], v[14:15], v[216:217], v[216:217] op_sel:[0,1,1] op_sel_hi:[1,1,1] clamp
	v_pk_fma_f32 v[16:17], v[16:17], v[216:217], v[216:217] op_sel:[0,1,1] op_sel_hi:[1,1,1] clamp
	v_rcp_f32_e32 v2, v2
	v_rcp_f32_e32 v3, v3
	v_rcp_f32_e32 v4, v4
	v_rcp_f32_e32 v5, v5
	v_rcp_f32_e32 v6, v6
	v_rcp_f32_e32 v7, v7
	v_rcp_f32_e32 v8, v8
	v_rcp_f32_e32 v9, v9
	v_rcp_f32_e32 v10, v10
	v_rcp_f32_e32 v11, v11
	v_rcp_f32_e32 v12, v12
	v_rcp_f32_e32 v13, v13
	v_rcp_f32_e32 v14, v14
	v_rcp_f32_e32 v15, v15
	v_rcp_f32_e32 v16, v16
	v_rcp_f32_e32 v17, v17
	v_cvt_pk_u8_f32 v22, v2, 0, 0
	v_cvt_pk_u8_f32 v23, v6, 0, 0
	v_cvt_pk_u8_f32 v24, v10, 0, 0
	v_cvt_pk_u8_f32 v25, v14, 0, 0
	v_cvt_pk_u8_f32 v22, v3, 1, v22
	v_cvt_pk_u8_f32 v23, v7, 1, v23
	v_cvt_pk_u8_f32 v24, v11, 1, v24
	v_cvt_pk_u8_f32 v25, v15, 1, v25
	v_cvt_pk_u8_f32 v22, v4, 2, v22
	v_cvt_pk_u8_f32 v23, v8, 2, v23
	v_cvt_pk_u8_f32 v24, v12, 2, v24
	v_cvt_pk_u8_f32 v25, v16, 2, v25
	v_cvt_pk_u8_f32 v22, v5, 3, v22
	v_cvt_pk_u8_f32 v23, v9, 3, v23
	v_cvt_pk_u8_f32 v24, v13, 3, v24
	v_cvt_pk_u8_f32 v25, v17, 3, v25
	global_store_dwordx4 v[0:1], v[22:25], off offset:3072 nt
	v_pk_mul_f32 v[2:3], v[98:99], v[28:29]
	v_pk_mul_f32 v[4:5], v[100:101], v[28:29]
	v_pk_mul_f32 v[6:7], v[94:95], v[28:29]
	v_pk_mul_f32 v[8:9], v[96:97], v[28:29]
	v_pk_mul_f32 v[10:11], v[90:91], v[28:29]
	v_pk_mul_f32 v[12:13], v[92:93], v[28:29]
	v_pk_mul_f32 v[14:15], v[86:87], v[28:29]
	v_pk_mul_f32 v[16:17], v[88:89], v[28:29]
	v_exp_f32_e32 v2, v2
	v_exp_f32_e32 v3, v3
	v_exp_f32_e32 v4, v4
	v_exp_f32_e32 v5, v5
	v_exp_f32_e32 v6, v6
	v_exp_f32_e32 v7, v7
	v_exp_f32_e32 v8, v8
	v_exp_f32_e32 v9, v9
	v_exp_f32_e32 v10, v10
	v_exp_f32_e32 v11, v11
	v_exp_f32_e32 v12, v12
	v_exp_f32_e32 v13, v13
	v_exp_f32_e32 v14, v14
	v_exp_f32_e32 v15, v15
	v_exp_f32_e32 v16, v16
	v_exp_f32_e32 v17, v17
	v_pk_fma_f32 v[2:3], v[2:3], v[216:217], v[216:217] op_sel:[0,1,1] op_sel_hi:[1,1,1] clamp
	v_pk_fma_f32 v[4:5], v[4:5], v[216:217], v[216:217] op_sel:[0,1,1] op_sel_hi:[1,1,1] clamp
	v_pk_fma_f32 v[6:7], v[6:7], v[216:217], v[216:217] op_sel:[0,1,1] op_sel_hi:[1,1,1] clamp
	v_pk_fma_f32 v[8:9], v[8:9], v[216:217], v[216:217] op_sel:[0,1,1] op_sel_hi:[1,1,1] clamp
	v_pk_fma_f32 v[10:11], v[10:11], v[216:217], v[216:217] op_sel:[0,1,1] op_sel_hi:[1,1,1] clamp
	v_pk_fma_f32 v[12:13], v[12:13], v[216:217], v[216:217] op_sel:[0,1,1] op_sel_hi:[1,1,1] clamp
	v_pk_fma_f32 v[14:15], v[14:15], v[216:217], v[216:217] op_sel:[0,1,1] op_sel_hi:[1,1,1] clamp
	v_pk_fma_f32 v[16:17], v[16:17], v[216:217], v[216:217] op_sel:[0,1,1] op_sel_hi:[1,1,1] clamp
	v_rcp_f32_e32 v2, v2
	v_rcp_f32_e32 v3, v3
	v_rcp_f32_e32 v4, v4
	v_rcp_f32_e32 v5, v5
	v_rcp_f32_e32 v6, v6
	v_rcp_f32_e32 v7, v7
	v_rcp_f32_e32 v8, v8
	v_rcp_f32_e32 v9, v9
	v_rcp_f32_e32 v10, v10
	v_rcp_f32_e32 v11, v11
	v_rcp_f32_e32 v12, v12
	v_rcp_f32_e32 v13, v13
	v_rcp_f32_e32 v14, v14
	v_rcp_f32_e32 v15, v15
	v_rcp_f32_e32 v16, v16
	v_rcp_f32_e32 v17, v17
	v_cvt_pk_u8_f32 v18, v2, 0, 0
	v_cvt_pk_u8_f32 v19, v6, 0, 0
	v_cvt_pk_u8_f32 v20, v10, 0, 0
	v_cvt_pk_u8_f32 v21, v14, 0, 0
	v_cvt_pk_u8_f32 v18, v3, 1, v18
	v_cvt_pk_u8_f32 v19, v7, 1, v19
	v_cvt_pk_u8_f32 v20, v11, 1, v20
	v_cvt_pk_u8_f32 v21, v15, 1, v21
	v_cvt_pk_u8_f32 v18, v4, 2, v18
	v_cvt_pk_u8_f32 v19, v8, 2, v19
	v_cvt_pk_u8_f32 v20, v12, 2, v20
	v_cvt_pk_u8_f32 v21, v16, 2, v21
	v_cvt_pk_u8_f32 v18, v5, 3, v18
	v_cvt_pk_u8_f32 v19, v9, 3, v19
	v_cvt_pk_u8_f32 v20, v13, 3, v20
	v_cvt_pk_u8_f32 v21, v17, 3, v21
	global_store_dwordx4 v[26:27], v[18:21], off nt
	v_pk_mul_f32 v[2:3], v[82:83], v[28:29]
	v_pk_mul_f32 v[4:5], v[84:85], v[28:29]
	v_pk_mul_f32 v[6:7], v[78:79], v[28:29]
	v_pk_mul_f32 v[8:9], v[80:81], v[28:29]
	v_pk_mul_f32 v[10:11], v[74:75], v[28:29]
	v_pk_mul_f32 v[12:13], v[76:77], v[28:29]
	v_pk_mul_f32 v[14:15], v[70:71], v[28:29]
	v_pk_mul_f32 v[16:17], v[72:73], v[28:29]
	v_exp_f32_e32 v2, v2
	v_exp_f32_e32 v3, v3
	v_exp_f32_e32 v4, v4
	v_exp_f32_e32 v5, v5
	v_exp_f32_e32 v6, v6
	v_exp_f32_e32 v7, v7
	v_exp_f32_e32 v8, v8
	v_exp_f32_e32 v9, v9
	v_exp_f32_e32 v10, v10
	v_exp_f32_e32 v11, v11
	v_exp_f32_e32 v12, v12
	v_exp_f32_e32 v13, v13
	v_exp_f32_e32 v14, v14
	v_exp_f32_e32 v15, v15
	v_exp_f32_e32 v16, v16
	v_exp_f32_e32 v17, v17
	v_pk_fma_f32 v[2:3], v[2:3], v[216:217], v[216:217] op_sel:[0,1,1] op_sel_hi:[1,1,1] clamp
	v_pk_fma_f32 v[4:5], v[4:5], v[216:217], v[216:217] op_sel:[0,1,1] op_sel_hi:[1,1,1] clamp
	v_pk_fma_f32 v[6:7], v[6:7], v[216:217], v[216:217] op_sel:[0,1,1] op_sel_hi:[1,1,1] clamp
	v_pk_fma_f32 v[8:9], v[8:9], v[216:217], v[216:217] op_sel:[0,1,1] op_sel_hi:[1,1,1] clamp
	v_pk_fma_f32 v[10:11], v[10:11], v[216:217], v[216:217] op_sel:[0,1,1] op_sel_hi:[1,1,1] clamp
	v_pk_fma_f32 v[12:13], v[12:13], v[216:217], v[216:217] op_sel:[0,1,1] op_sel_hi:[1,1,1] clamp
	v_pk_fma_f32 v[14:15], v[14:15], v[216:217], v[216:217] op_sel:[0,1,1] op_sel_hi:[1,1,1] clamp
	v_pk_fma_f32 v[16:17], v[16:17], v[216:217], v[216:217] op_sel:[0,1,1] op_sel_hi:[1,1,1] clamp
	v_rcp_f32_e32 v2, v2
	v_rcp_f32_e32 v3, v3
	v_rcp_f32_e32 v4, v4
	v_rcp_f32_e32 v5, v5
	v_rcp_f32_e32 v6, v6
	v_rcp_f32_e32 v7, v7
	v_rcp_f32_e32 v8, v8
	v_rcp_f32_e32 v9, v9
	v_rcp_f32_e32 v10, v10
	v_rcp_f32_e32 v11, v11
	v_rcp_f32_e32 v12, v12
	v_rcp_f32_e32 v13, v13
	v_rcp_f32_e32 v14, v14
	v_rcp_f32_e32 v15, v15
	v_rcp_f32_e32 v16, v16
	v_rcp_f32_e32 v17, v17
	v_cvt_pk_u8_f32 v22, v2, 0, 0
	v_cvt_pk_u8_f32 v23, v6, 0, 0
	v_cvt_pk_u8_f32 v24, v10, 0, 0
	v_cvt_pk_u8_f32 v25, v14, 0, 0
	v_cvt_pk_u8_f32 v22, v3, 1, v22
	v_cvt_pk_u8_f32 v23, v7, 1, v23
	v_cvt_pk_u8_f32 v24, v11, 1, v24
	v_cvt_pk_u8_f32 v25, v15, 1, v25
	v_cvt_pk_u8_f32 v22, v4, 2, v22
	v_cvt_pk_u8_f32 v23, v8, 2, v23
	v_cvt_pk_u8_f32 v24, v12, 2, v24
	v_cvt_pk_u8_f32 v25, v16, 2, v25
	v_cvt_pk_u8_f32 v22, v5, 3, v22
	v_cvt_pk_u8_f32 v23, v9, 3, v23
	v_cvt_pk_u8_f32 v24, v13, 3, v24
	v_cvt_pk_u8_f32 v25, v17, 3, v25
	global_store_dwordx4 v[26:27], v[22:25], off offset:1024 nt
	v_pk_mul_f32 v[2:3], v[66:67], v[28:29]
	v_pk_mul_f32 v[4:5], v[68:69], v[28:29]
	v_pk_mul_f32 v[6:7], v[62:63], v[28:29]
	v_pk_mul_f32 v[8:9], v[64:65], v[28:29]
	v_pk_mul_f32 v[10:11], v[58:59], v[28:29]
	v_pk_mul_f32 v[12:13], v[60:61], v[28:29]
	v_pk_mul_f32 v[14:15], v[54:55], v[28:29]
	v_pk_mul_f32 v[16:17], v[56:57], v[28:29]
	v_exp_f32_e32 v2, v2
	v_exp_f32_e32 v3, v3
	v_exp_f32_e32 v4, v4
	v_exp_f32_e32 v5, v5
	v_exp_f32_e32 v6, v6
	v_exp_f32_e32 v7, v7
	v_exp_f32_e32 v8, v8
	v_exp_f32_e32 v9, v9
	v_exp_f32_e32 v10, v10
	v_exp_f32_e32 v11, v11
	v_exp_f32_e32 v12, v12
	v_exp_f32_e32 v13, v13
	v_exp_f32_e32 v14, v14
	v_exp_f32_e32 v15, v15
	v_exp_f32_e32 v16, v16
	v_exp_f32_e32 v17, v17
	v_pk_fma_f32 v[2:3], v[2:3], v[216:217], v[216:217] op_sel:[0,1,1] op_sel_hi:[1,1,1] clamp
	v_pk_fma_f32 v[4:5], v[4:5], v[216:217], v[216:217] op_sel:[0,1,1] op_sel_hi:[1,1,1] clamp
	v_pk_fma_f32 v[6:7], v[6:7], v[216:217], v[216:217] op_sel:[0,1,1] op_sel_hi:[1,1,1] clamp
	v_pk_fma_f32 v[8:9], v[8:9], v[216:217], v[216:217] op_sel:[0,1,1] op_sel_hi:[1,1,1] clamp
	v_pk_fma_f32 v[10:11], v[10:11], v[216:217], v[216:217] op_sel:[0,1,1] op_sel_hi:[1,1,1] clamp
	v_pk_fma_f32 v[12:13], v[12:13], v[216:217], v[216:217] op_sel:[0,1,1] op_sel_hi:[1,1,1] clamp
	v_pk_fma_f32 v[14:15], v[14:15], v[216:217], v[216:217] op_sel:[0,1,1] op_sel_hi:[1,1,1] clamp
	v_pk_fma_f32 v[16:17], v[16:17], v[216:217], v[216:217] op_sel:[0,1,1] op_sel_hi:[1,1,1] clamp
	v_rcp_f32_e32 v2, v2
	v_rcp_f32_e32 v3, v3
	v_rcp_f32_e32 v4, v4
	v_rcp_f32_e32 v5, v5
	v_rcp_f32_e32 v6, v6
	v_rcp_f32_e32 v7, v7
	v_rcp_f32_e32 v8, v8
	v_rcp_f32_e32 v9, v9
	v_rcp_f32_e32 v10, v10
	v_rcp_f32_e32 v11, v11
	v_rcp_f32_e32 v12, v12
	v_rcp_f32_e32 v13, v13
	v_rcp_f32_e32 v14, v14
	v_rcp_f32_e32 v15, v15
	v_rcp_f32_e32 v16, v16
	v_rcp_f32_e32 v17, v17
	v_cvt_pk_u8_f32 v18, v2, 0, 0
	v_cvt_pk_u8_f32 v19, v6, 0, 0
	v_cvt_pk_u8_f32 v20, v10, 0, 0
	v_cvt_pk_u8_f32 v21, v14, 0, 0
	v_cvt_pk_u8_f32 v18, v3, 1, v18
	v_cvt_pk_u8_f32 v19, v7, 1, v19
	v_cvt_pk_u8_f32 v20, v11, 1, v20
	v_cvt_pk_u8_f32 v21, v15, 1, v21
	v_cvt_pk_u8_f32 v18, v4, 2, v18
	v_cvt_pk_u8_f32 v19, v8, 2, v19
	v_cvt_pk_u8_f32 v20, v12, 2, v20
	v_cvt_pk_u8_f32 v21, v16, 2, v21
	v_cvt_pk_u8_f32 v18, v5, 3, v18
	v_cvt_pk_u8_f32 v19, v9, 3, v19
	v_cvt_pk_u8_f32 v20, v13, 3, v20
	v_cvt_pk_u8_f32 v21, v17, 3, v21
	global_store_dwordx4 v[26:27], v[18:21], off offset:2048 nt
	v_pk_mul_f32 v[2:3], v[50:51], v[28:29]
	v_pk_mul_f32 v[4:5], v[52:53], v[28:29]
	v_pk_mul_f32 v[6:7], v[46:47], v[28:29]
	v_pk_mul_f32 v[8:9], v[48:49], v[28:29]
	v_pk_mul_f32 v[10:11], v[42:43], v[28:29]
	v_pk_mul_f32 v[12:13], v[44:45], v[28:29]
	v_pk_mul_f32 v[14:15], v[38:39], v[28:29]
	v_pk_mul_f32 v[16:17], v[40:41], v[28:29]
	v_exp_f32_e32 v2, v2
	v_exp_f32_e32 v3, v3
	v_exp_f32_e32 v4, v4
	v_exp_f32_e32 v5, v5
	v_exp_f32_e32 v6, v6
	v_exp_f32_e32 v7, v7
	v_exp_f32_e32 v8, v8
	v_exp_f32_e32 v9, v9
	v_exp_f32_e32 v10, v10
	v_exp_f32_e32 v11, v11
	v_exp_f32_e32 v12, v12
	v_exp_f32_e32 v13, v13
	v_exp_f32_e32 v14, v14
	v_exp_f32_e32 v15, v15
	v_exp_f32_e32 v16, v16
	v_exp_f32_e32 v17, v17
	v_pk_fma_f32 v[2:3], v[2:3], v[216:217], v[216:217] op_sel:[0,1,1] op_sel_hi:[1,1,1] clamp
	v_pk_fma_f32 v[4:5], v[4:5], v[216:217], v[216:217] op_sel:[0,1,1] op_sel_hi:[1,1,1] clamp
	v_pk_fma_f32 v[6:7], v[6:7], v[216:217], v[216:217] op_sel:[0,1,1] op_sel_hi:[1,1,1] clamp
	v_pk_fma_f32 v[8:9], v[8:9], v[216:217], v[216:217] op_sel:[0,1,1] op_sel_hi:[1,1,1] clamp
	v_pk_fma_f32 v[10:11], v[10:11], v[216:217], v[216:217] op_sel:[0,1,1] op_sel_hi:[1,1,1] clamp
	v_pk_fma_f32 v[12:13], v[12:13], v[216:217], v[216:217] op_sel:[0,1,1] op_sel_hi:[1,1,1] clamp
	v_pk_fma_f32 v[14:15], v[14:15], v[216:217], v[216:217] op_sel:[0,1,1] op_sel_hi:[1,1,1] clamp
	v_pk_fma_f32 v[16:17], v[16:17], v[216:217], v[216:217] op_sel:[0,1,1] op_sel_hi:[1,1,1] clamp
	v_rcp_f32_e32 v2, v2
	v_rcp_f32_e32 v3, v3
	v_rcp_f32_e32 v4, v4
	v_rcp_f32_e32 v5, v5
	v_rcp_f32_e32 v6, v6
	v_rcp_f32_e32 v7, v7
	v_rcp_f32_e32 v8, v8
	v_rcp_f32_e32 v9, v9
	v_rcp_f32_e32 v10, v10
	v_rcp_f32_e32 v11, v11
	v_rcp_f32_e32 v12, v12
	v_rcp_f32_e32 v13, v13
	v_rcp_f32_e32 v14, v14
	v_rcp_f32_e32 v15, v15
	v_rcp_f32_e32 v16, v16
	v_rcp_f32_e32 v17, v17
	v_cvt_pk_u8_f32 v22, v2, 0, 0
	v_cvt_pk_u8_f32 v23, v6, 0, 0
	v_cvt_pk_u8_f32 v24, v10, 0, 0
	v_cvt_pk_u8_f32 v25, v14, 0, 0
	v_cvt_pk_u8_f32 v22, v3, 1, v22
	v_cvt_pk_u8_f32 v23, v7, 1, v23
	v_cvt_pk_u8_f32 v24, v11, 1, v24
	v_cvt_pk_u8_f32 v25, v15, 1, v25
	v_cvt_pk_u8_f32 v22, v4, 2, v22
	v_cvt_pk_u8_f32 v23, v8, 2, v23
	v_cvt_pk_u8_f32 v24, v12, 2, v24
	v_cvt_pk_u8_f32 v25, v16, 2, v25
	v_cvt_pk_u8_f32 v22, v5, 3, v22
	v_cvt_pk_u8_f32 v23, v9, 3, v23
	v_cvt_pk_u8_f32 v24, v13, 3, v24
	v_cvt_pk_u8_f32 v25, v17, 3, v25
	global_store_dwordx4 v[26:27], v[22:25], off offset:3072 nt
	s_andn2_b64 vcc, exec, s[64:65]
	s_mov_b64 s[8:9], -1
	s_cbranch_vccnz .LBB0_310
	s_branch .LBB0_367

.LBB0_517:
	s_and_b64 vcc, exec, s[8:9]
	s_cbranch_vccz .LBB0_538
	s_lshl_b32 s9, s72, 2
	s_add_i32 s0, s72, -16
	s_lshl_b32 s8, s73, 4
	s_and_b32 s9, s9, 12
	s_or_b32 s8, s9, s8
	s_lshr_b32 s0, s0, 2
	s_add_i32 s8, s8, s0
	s_ashr_i32 s9, s8, 31
	s_lshl_b64 s[8:9], s[8:9], 16
	v_lshl_add_u64 v[0:1], v[190:191], 0, s[8:9]
	s_mov_b64 s[8:9], 0x1000
	v_lshl_add_u64 v[26:27], v[0:1], 0, s[8:9]
	v_mov_b32_e32 v28, 0xbfb8aa3b
	v_mov_b32_e32 v29, 0xbfb8aa3b
	v_pk_mul_f32 v[2:3], v[162:163], v[28:29]
	v_pk_mul_f32 v[4:5], v[164:165], v[28:29]
	v_pk_mul_f32 v[6:7], v[158:159], v[28:29]
	v_pk_mul_f32 v[8:9], v[160:161], v[28:29]
	v_pk_mul_f32 v[10:11], v[154:155], v[28:29]
	v_pk_mul_f32 v[12:13], v[156:157], v[28:29]
	v_pk_mul_f32 v[14:15], v[150:151], v[28:29]
	v_pk_mul_f32 v[16:17], v[152:153], v[28:29]
	v_exp_f32_e32 v2, v2
	v_exp_f32_e32 v3, v3
	v_exp_f32_e32 v4, v4
	v_exp_f32_e32 v5, v5
	v_exp_f32_e32 v6, v6
	v_exp_f32_e32 v7, v7
	v_exp_f32_e32 v8, v8
	v_exp_f32_e32 v9, v9
	v_exp_f32_e32 v10, v10
	v_exp_f32_e32 v11, v11
	v_exp_f32_e32 v12, v12
	v_exp_f32_e32 v13, v13
	v_exp_f32_e32 v14, v14
	v_exp_f32_e32 v15, v15
	v_exp_f32_e32 v16, v16
	v_exp_f32_e32 v17, v17
	v_pk_fma_f32 v[2:3], v[2:3], v[216:217], v[216:217] op_sel:[0,1,1] op_sel_hi:[1,1,1] clamp
	v_pk_fma_f32 v[4:5], v[4:5], v[216:217], v[216:217] op_sel:[0,1,1] op_sel_hi:[1,1,1] clamp
	v_pk_fma_f32 v[6:7], v[6:7], v[216:217], v[216:217] op_sel:[0,1,1] op_sel_hi:[1,1,1] clamp
	v_pk_fma_f32 v[8:9], v[8:9], v[216:217], v[216:217] op_sel:[0,1,1] op_sel_hi:[1,1,1] clamp
	v_pk_fma_f32 v[10:11], v[10:11], v[216:217], v[216:217] op_sel:[0,1,1] op_sel_hi:[1,1,1] clamp
	v_pk_fma_f32 v[12:13], v[12:13], v[216:217], v[216:217] op_sel:[0,1,1] op_sel_hi:[1,1,1] clamp
	v_pk_fma_f32 v[14:15], v[14:15], v[216:217], v[216:217] op_sel:[0,1,1] op_sel_hi:[1,1,1] clamp
	v_pk_fma_f32 v[16:17], v[16:17], v[216:217], v[216:217] op_sel:[0,1,1] op_sel_hi:[1,1,1] clamp
	v_rcp_f32_e32 v2, v2
	v_rcp_f32_e32 v3, v3
	v_rcp_f32_e32 v4, v4
	v_rcp_f32_e32 v5, v5
	v_rcp_f32_e32 v6, v6
	v_rcp_f32_e32 v7, v7
	v_rcp_f32_e32 v8, v8
	v_rcp_f32_e32 v9, v9
	v_rcp_f32_e32 v10, v10
	v_rcp_f32_e32 v11, v11
	v_rcp_f32_e32 v12, v12
	v_rcp_f32_e32 v13, v13
	v_rcp_f32_e32 v14, v14
	v_rcp_f32_e32 v15, v15
	v_rcp_f32_e32 v16, v16
	v_rcp_f32_e32 v17, v17
	v_cvt_pk_u8_f32 v18, v2, 0, 0
	v_cvt_pk_u8_f32 v19, v6, 0, 0
	v_cvt_pk_u8_f32 v20, v10, 0, 0
	v_cvt_pk_u8_f32 v21, v14, 0, 0
	v_cvt_pk_u8_f32 v18, v3, 1, v18
	v_cvt_pk_u8_f32 v19, v7, 1, v19
	v_cvt_pk_u8_f32 v20, v11, 1, v20
	v_cvt_pk_u8_f32 v21, v15, 1, v21
	v_cvt_pk_u8_f32 v18, v4, 2, v18
	v_cvt_pk_u8_f32 v19, v8, 2, v19
	v_cvt_pk_u8_f32 v20, v12, 2, v20
	v_cvt_pk_u8_f32 v21, v16, 2, v21
	v_cvt_pk_u8_f32 v18, v5, 3, v18
	v_cvt_pk_u8_f32 v19, v9, 3, v19
	v_cvt_pk_u8_f32 v20, v13, 3, v20
	v_cvt_pk_u8_f32 v21, v17, 3, v21
	global_store_dwordx4 v[0:1], v[18:21], off nt
	v_pk_mul_f32 v[2:3], v[146:147], v[28:29]
	v_pk_mul_f32 v[4:5], v[148:149], v[28:29]
	v_pk_mul_f32 v[6:7], v[142:143], v[28:29]
	v_pk_mul_f32 v[8:9], v[144:145], v[28:29]
	v_pk_mul_f32 v[10:11], v[138:139], v[28:29]
	v_pk_mul_f32 v[12:13], v[140:141], v[28:29]
	v_pk_mul_f32 v[14:15], v[134:135], v[28:29]
	v_pk_mul_f32 v[16:17], v[136:137], v[28:29]
	v_exp_f32_e32 v2, v2
	v_exp_f32_e32 v3, v3
	v_exp_f32_e32 v4, v4
	v_exp_f32_e32 v5, v5
	v_exp_f32_e32 v6, v6
	v_exp_f32_e32 v7, v7
	v_exp_f32_e32 v8, v8
	v_exp_f32_e32 v9, v9
	v_exp_f32_e32 v10, v10
	v_exp_f32_e32 v11, v11
	v_exp_f32_e32 v12, v12
	v_exp_f32_e32 v13, v13
	v_exp_f32_e32 v14, v14
	v_exp_f32_e32 v15, v15
	v_exp_f32_e32 v16, v16
	v_exp_f32_e32 v17, v17
	v_pk_fma_f32 v[2:3], v[2:3], v[216:217], v[216:217] op_sel:[0,1,1] op_sel_hi:[1,1,1] clamp
	v_pk_fma_f32 v[4:5], v[4:5], v[216:217], v[216:217] op_sel:[0,1,1] op_sel_hi:[1,1,1] clamp
	v_pk_fma_f32 v[6:7], v[6:7], v[216:217], v[216:217] op_sel:[0,1,1] op_sel_hi:[1,1,1] clamp
	v_pk_fma_f32 v[8:9], v[8:9], v[216:217], v[216:217] op_sel:[0,1,1] op_sel_hi:[1,1,1] clamp
	v_pk_fma_f32 v[10:11], v[10:11], v[216:217], v[216:217] op_sel:[0,1,1] op_sel_hi:[1,1,1] clamp
	v_pk_fma_f32 v[12:13], v[12:13], v[216:217], v[216:217] op_sel:[0,1,1] op_sel_hi:[1,1,1] clamp
	v_pk_fma_f32 v[14:15], v[14:15], v[216:217], v[216:217] op_sel:[0,1,1] op_sel_hi:[1,1,1] clamp
	v_pk_fma_f32 v[16:17], v[16:17], v[216:217], v[216:217] op_sel:[0,1,1] op_sel_hi:[1,1,1] clamp
	v_rcp_f32_e32 v2, v2
	v_rcp_f32_e32 v3, v3
	v_rcp_f32_e32 v4, v4
	v_rcp_f32_e32 v5, v5
	v_rcp_f32_e32 v6, v6
	v_rcp_f32_e32 v7, v7
	v_rcp_f32_e32 v8, v8
	v_rcp_f32_e32 v9, v9
	v_rcp_f32_e32 v10, v10
	v_rcp_f32_e32 v11, v11
	v_rcp_f32_e32 v12, v12
	v_rcp_f32_e32 v13, v13
	v_rcp_f32_e32 v14, v14
	v_rcp_f32_e32 v15, v15
	v_rcp_f32_e32 v16, v16
	v_rcp_f32_e32 v17, v17
	v_cvt_pk_u8_f32 v22, v2, 0, 0
	v_cvt_pk_u8_f32 v23, v6, 0, 0
	v_cvt_pk_u8_f32 v24, v10, 0, 0
	v_cvt_pk_u8_f32 v25, v14, 0, 0
	v_cvt_pk_u8_f32 v22, v3, 1, v22
	v_cvt_pk_u8_f32 v23, v7, 1, v23
	v_cvt_pk_u8_f32 v24, v11, 1, v24
	v_cvt_pk_u8_f32 v25, v15, 1, v25
	v_cvt_pk_u8_f32 v22, v4, 2, v22
	v_cvt_pk_u8_f32 v23, v8, 2, v23
	v_cvt_pk_u8_f32 v24, v12, 2, v24
	v_cvt_pk_u8_f32 v25, v16, 2, v25
	v_cvt_pk_u8_f32 v22, v5, 3, v22
	v_cvt_pk_u8_f32 v23, v9, 3, v23
	v_cvt_pk_u8_f32 v24, v13, 3, v24
	v_cvt_pk_u8_f32 v25, v17, 3, v25
	global_store_dwordx4 v[0:1], v[22:25], off offset:1024 nt
	v_pk_mul_f32 v[2:3], v[130:131], v[28:29]
	v_pk_mul_f32 v[4:5], v[132:133], v[28:29]
	v_pk_mul_f32 v[6:7], v[126:127], v[28:29]
	v_pk_mul_f32 v[8:9], v[128:129], v[28:29]
	v_pk_mul_f32 v[10:11], v[122:123], v[28:29]
	v_pk_mul_f32 v[12:13], v[124:125], v[28:29]
	v_pk_mul_f32 v[14:15], v[118:119], v[28:29]
	v_pk_mul_f32 v[16:17], v[120:121], v[28:29]
	v_exp_f32_e32 v2, v2
	v_exp_f32_e32 v3, v3
	v_exp_f32_e32 v4, v4
	v_exp_f32_e32 v5, v5
	v_exp_f32_e32 v6, v6
	v_exp_f32_e32 v7, v7
	v_exp_f32_e32 v8, v8
	v_exp_f32_e32 v9, v9
	v_exp_f32_e32 v10, v10
	v_exp_f32_e32 v11, v11
	v_exp_f32_e32 v12, v12
	v_exp_f32_e32 v13, v13
	v_exp_f32_e32 v14, v14
	v_exp_f32_e32 v15, v15
	v_exp_f32_e32 v16, v16
	v_exp_f32_e32 v17, v17
	v_pk_fma_f32 v[2:3], v[2:3], v[216:217], v[216:217] op_sel:[0,1,1] op_sel_hi:[1,1,1] clamp
	v_pk_fma_f32 v[4:5], v[4:5], v[216:217], v[216:217] op_sel:[0,1,1] op_sel_hi:[1,1,1] clamp
	v_pk_fma_f32 v[6:7], v[6:7], v[216:217], v[216:217] op_sel:[0,1,1] op_sel_hi:[1,1,1] clamp
	v_pk_fma_f32 v[8:9], v[8:9], v[216:217], v[216:217] op_sel:[0,1,1] op_sel_hi:[1,1,1] clamp
	v_pk_fma_f32 v[10:11], v[10:11], v[216:217], v[216:217] op_sel:[0,1,1] op_sel_hi:[1,1,1] clamp
	v_pk_fma_f32 v[12:13], v[12:13], v[216:217], v[216:217] op_sel:[0,1,1] op_sel_hi:[1,1,1] clamp
	v_pk_fma_f32 v[14:15], v[14:15], v[216:217], v[216:217] op_sel:[0,1,1] op_sel_hi:[1,1,1] clamp
	v_pk_fma_f32 v[16:17], v[16:17], v[216:217], v[216:217] op_sel:[0,1,1] op_sel_hi:[1,1,1] clamp
	v_rcp_f32_e32 v2, v2
	v_rcp_f32_e32 v3, v3
	v_rcp_f32_e32 v4, v4
	v_rcp_f32_e32 v5, v5
	v_rcp_f32_e32 v6, v6
	v_rcp_f32_e32 v7, v7
	v_rcp_f32_e32 v8, v8
	v_rcp_f32_e32 v9, v9
	v_rcp_f32_e32 v10, v10
	v_rcp_f32_e32 v11, v11
	v_rcp_f32_e32 v12, v12
	v_rcp_f32_e32 v13, v13
	v_rcp_f32_e32 v14, v14
	v_rcp_f32_e32 v15, v15
	v_rcp_f32_e32 v16, v16
	v_rcp_f32_e32 v17, v17
	v_cvt_pk_u8_f32 v18, v2, 0, 0
	v_cvt_pk_u8_f32 v19, v6, 0, 0
	v_cvt_pk_u8_f32 v20, v10, 0, 0
	v_cvt_pk_u8_f32 v21, v14, 0, 0
	v_cvt_pk_u8_f32 v18, v3, 1, v18
	v_cvt_pk_u8_f32 v19, v7, 1, v19
	v_cvt_pk_u8_f32 v20, v11, 1, v20
	v_cvt_pk_u8_f32 v21, v15, 1, v21
	v_cvt_pk_u8_f32 v18, v4, 2, v18
	v_cvt_pk_u8_f32 v19, v8, 2, v19
	v_cvt_pk_u8_f32 v20, v12, 2, v20
	v_cvt_pk_u8_f32 v21, v16, 2, v21
	v_cvt_pk_u8_f32 v18, v5, 3, v18
	v_cvt_pk_u8_f32 v19, v9, 3, v19
	v_cvt_pk_u8_f32 v20, v13, 3, v20
	v_cvt_pk_u8_f32 v21, v17, 3, v21
	global_store_dwordx4 v[0:1], v[18:21], off offset:2048 nt
	v_pk_mul_f32 v[2:3], v[114:115], v[28:29]
	v_pk_mul_f32 v[4:5], v[116:117], v[28:29]
	v_pk_mul_f32 v[6:7], v[110:111], v[28:29]
	v_pk_mul_f32 v[8:9], v[112:113], v[28:29]
	v_pk_mul_f32 v[10:11], v[106:107], v[28:29]
	v_pk_mul_f32 v[12:13], v[108:109], v[28:29]
	v_pk_mul_f32 v[14:15], v[102:103], v[28:29]
	v_pk_mul_f32 v[16:17], v[104:105], v[28:29]
	v_exp_f32_e32 v2, v2
	v_exp_f32_e32 v3, v3
	v_exp_f32_e32 v4, v4
	v_exp_f32_e32 v5, v5
	v_exp_f32_e32 v6, v6
	v_exp_f32_e32 v7, v7
	v_exp_f32_e32 v8, v8
	v_exp_f32_e32 v9, v9
	v_exp_f32_e32 v10, v10
	v_exp_f32_e32 v11, v11
	v_exp_f32_e32 v12, v12
	v_exp_f32_e32 v13, v13
	v_exp_f32_e32 v14, v14
	v_exp_f32_e32 v15, v15
	v_exp_f32_e32 v16, v16
	v_exp_f32_e32 v17, v17
	v_pk_fma_f32 v[2:3], v[2:3], v[216:217], v[216:217] op_sel:[0,1,1] op_sel_hi:[1,1,1] clamp
	v_pk_fma_f32 v[4:5], v[4:5], v[216:217], v[216:217] op_sel:[0,1,1] op_sel_hi:[1,1,1] clamp
	v_pk_fma_f32 v[6:7], v[6:7], v[216:217], v[216:217] op_sel:[0,1,1] op_sel_hi:[1,1,1] clamp
	v_pk_fma_f32 v[8:9], v[8:9], v[216:217], v[216:217] op_sel:[0,1,1] op_sel_hi:[1,1,1] clamp
	v_pk_fma_f32 v[10:11], v[10:11], v[216:217], v[216:217] op_sel:[0,1,1] op_sel_hi:[1,1,1] clamp
	v_pk_fma_f32 v[12:13], v[12:13], v[216:217], v[216:217] op_sel:[0,1,1] op_sel_hi:[1,1,1] clamp
	v_pk_fma_f32 v[14:15], v[14:15], v[216:217], v[216:217] op_sel:[0,1,1] op_sel_hi:[1,1,1] clamp
	v_pk_fma_f32 v[16:17], v[16:17], v[216:217], v[216:217] op_sel:[0,1,1] op_sel_hi:[1,1,1] clamp
	v_rcp_f32_e32 v2, v2
	v_rcp_f32_e32 v3, v3
	v_rcp_f32_e32 v4, v4
	v_rcp_f32_e32 v5, v5
	v_rcp_f32_e32 v6, v6
	v_rcp_f32_e32 v7, v7
	v_rcp_f32_e32 v8, v8
	v_rcp_f32_e32 v9, v9
	v_rcp_f32_e32 v10, v10
	v_rcp_f32_e32 v11, v11
	v_rcp_f32_e32 v12, v12
	v_rcp_f32_e32 v13, v13
	v_rcp_f32_e32 v14, v14
	v_rcp_f32_e32 v15, v15
	v_rcp_f32_e32 v16, v16
	v_rcp_f32_e32 v17, v17
	v_cvt_pk_u8_f32 v22, v2, 0, 0
	v_cvt_pk_u8_f32 v23, v6, 0, 0
	v_cvt_pk_u8_f32 v24, v10, 0, 0
	v_cvt_pk_u8_f32 v25, v14, 0, 0
	v_cvt_pk_u8_f32 v22, v3, 1, v22
	v_cvt_pk_u8_f32 v23, v7, 1, v23
	v_cvt_pk_u8_f32 v24, v11, 1, v24
	v_cvt_pk_u8_f32 v25, v15, 1, v25
	v_cvt_pk_u8_f32 v22, v4, 2, v22
	v_cvt_pk_u8_f32 v23, v8, 2, v23
	v_cvt_pk_u8_f32 v24, v12, 2, v24
	v_cvt_pk_u8_f32 v25, v16, 2, v25
	v_cvt_pk_u8_f32 v22, v5, 3, v22
	v_cvt_pk_u8_f32 v23, v9, 3, v23
	v_cvt_pk_u8_f32 v24, v13, 3, v24
	v_cvt_pk_u8_f32 v25, v17, 3, v25
	global_store_dwordx4 v[0:1], v[22:25], off offset:3072 nt
	v_pk_mul_f32 v[2:3], v[98:99], v[28:29]
	v_pk_mul_f32 v[4:5], v[100:101], v[28:29]
	v_pk_mul_f32 v[6:7], v[94:95], v[28:29]
	v_pk_mul_f32 v[8:9], v[96:97], v[28:29]
	v_pk_mul_f32 v[10:11], v[90:91], v[28:29]
	v_pk_mul_f32 v[12:13], v[92:93], v[28:29]
	v_pk_mul_f32 v[14:15], v[86:87], v[28:29]
	v_pk_mul_f32 v[16:17], v[88:89], v[28:29]
	v_exp_f32_e32 v2, v2
	v_exp_f32_e32 v3, v3
	v_exp_f32_e32 v4, v4
	v_exp_f32_e32 v5, v5
	v_exp_f32_e32 v6, v6
	v_exp_f32_e32 v7, v7
	v_exp_f32_e32 v8, v8
	v_exp_f32_e32 v9, v9
	v_exp_f32_e32 v10, v10
	v_exp_f32_e32 v11, v11
	v_exp_f32_e32 v12, v12
	v_exp_f32_e32 v13, v13
	v_exp_f32_e32 v14, v14
	v_exp_f32_e32 v15, v15
	v_exp_f32_e32 v16, v16
	v_exp_f32_e32 v17, v17
	v_pk_fma_f32 v[2:3], v[2:3], v[216:217], v[216:217] op_sel:[0,1,1] op_sel_hi:[1,1,1] clamp
	v_pk_fma_f32 v[4:5], v[4:5], v[216:217], v[216:217] op_sel:[0,1,1] op_sel_hi:[1,1,1] clamp
	v_pk_fma_f32 v[6:7], v[6:7], v[216:217], v[216:217] op_sel:[0,1,1] op_sel_hi:[1,1,1] clamp
	v_pk_fma_f32 v[8:9], v[8:9], v[216:217], v[216:217] op_sel:[0,1,1] op_sel_hi:[1,1,1] clamp
	v_pk_fma_f32 v[10:11], v[10:11], v[216:217], v[216:217] op_sel:[0,1,1] op_sel_hi:[1,1,1] clamp
	v_pk_fma_f32 v[12:13], v[12:13], v[216:217], v[216:217] op_sel:[0,1,1] op_sel_hi:[1,1,1] clamp
	v_pk_fma_f32 v[14:15], v[14:15], v[216:217], v[216:217] op_sel:[0,1,1] op_sel_hi:[1,1,1] clamp
	v_pk_fma_f32 v[16:17], v[16:17], v[216:217], v[216:217] op_sel:[0,1,1] op_sel_hi:[1,1,1] clamp
	v_rcp_f32_e32 v2, v2
	v_rcp_f32_e32 v3, v3
	v_rcp_f32_e32 v4, v4
	v_rcp_f32_e32 v5, v5
	v_rcp_f32_e32 v6, v6
	v_rcp_f32_e32 v7, v7
	v_rcp_f32_e32 v8, v8
	v_rcp_f32_e32 v9, v9
	v_rcp_f32_e32 v10, v10
	v_rcp_f32_e32 v11, v11
	v_rcp_f32_e32 v12, v12
	v_rcp_f32_e32 v13, v13
	v_rcp_f32_e32 v14, v14
	v_rcp_f32_e32 v15, v15
	v_rcp_f32_e32 v16, v16
	v_rcp_f32_e32 v17, v17
	v_cvt_pk_u8_f32 v18, v2, 0, 0
	v_cvt_pk_u8_f32 v19, v6, 0, 0
	v_cvt_pk_u8_f32 v20, v10, 0, 0
	v_cvt_pk_u8_f32 v21, v14, 0, 0
	v_cvt_pk_u8_f32 v18, v3, 1, v18
	v_cvt_pk_u8_f32 v19, v7, 1, v19
	v_cvt_pk_u8_f32 v20, v11, 1, v20
	v_cvt_pk_u8_f32 v21, v15, 1, v21
	v_cvt_pk_u8_f32 v18, v4, 2, v18
	v_cvt_pk_u8_f32 v19, v8, 2, v19
	v_cvt_pk_u8_f32 v20, v12, 2, v20
	v_cvt_pk_u8_f32 v21, v16, 2, v21
	v_cvt_pk_u8_f32 v18, v5, 3, v18
	v_cvt_pk_u8_f32 v19, v9, 3, v19
	v_cvt_pk_u8_f32 v20, v13, 3, v20
	v_cvt_pk_u8_f32 v21, v17, 3, v21
	global_store_dwordx4 v[26:27], v[18:21], off nt
	v_pk_mul_f32 v[2:3], v[82:83], v[28:29]
	v_pk_mul_f32 v[4:5], v[84:85], v[28:29]
	v_pk_mul_f32 v[6:7], v[78:79], v[28:29]
	v_pk_mul_f32 v[8:9], v[80:81], v[28:29]
	v_pk_mul_f32 v[10:11], v[74:75], v[28:29]
	v_pk_mul_f32 v[12:13], v[76:77], v[28:29]
	v_pk_mul_f32 v[14:15], v[70:71], v[28:29]
	v_pk_mul_f32 v[16:17], v[72:73], v[28:29]
	v_exp_f32_e32 v2, v2
	v_exp_f32_e32 v3, v3
	v_exp_f32_e32 v4, v4
	v_exp_f32_e32 v5, v5
	v_exp_f32_e32 v6, v6
	v_exp_f32_e32 v7, v7
	v_exp_f32_e32 v8, v8
	v_exp_f32_e32 v9, v9
	v_exp_f32_e32 v10, v10
	v_exp_f32_e32 v11, v11
	v_exp_f32_e32 v12, v12
	v_exp_f32_e32 v13, v13
	v_exp_f32_e32 v14, v14
	v_exp_f32_e32 v15, v15
	v_exp_f32_e32 v16, v16
	v_exp_f32_e32 v17, v17
	v_pk_fma_f32 v[2:3], v[2:3], v[216:217], v[216:217] op_sel:[0,1,1] op_sel_hi:[1,1,1] clamp
	v_pk_fma_f32 v[4:5], v[4:5], v[216:217], v[216:217] op_sel:[0,1,1] op_sel_hi:[1,1,1] clamp
	v_pk_fma_f32 v[6:7], v[6:7], v[216:217], v[216:217] op_sel:[0,1,1] op_sel_hi:[1,1,1] clamp
	v_pk_fma_f32 v[8:9], v[8:9], v[216:217], v[216:217] op_sel:[0,1,1] op_sel_hi:[1,1,1] clamp
	v_pk_fma_f32 v[10:11], v[10:11], v[216:217], v[216:217] op_sel:[0,1,1] op_sel_hi:[1,1,1] clamp
	v_pk_fma_f32 v[12:13], v[12:13], v[216:217], v[216:217] op_sel:[0,1,1] op_sel_hi:[1,1,1] clamp
	v_pk_fma_f32 v[14:15], v[14:15], v[216:217], v[216:217] op_sel:[0,1,1] op_sel_hi:[1,1,1] clamp
	v_pk_fma_f32 v[16:17], v[16:17], v[216:217], v[216:217] op_sel:[0,1,1] op_sel_hi:[1,1,1] clamp
	v_rcp_f32_e32 v2, v2
	v_rcp_f32_e32 v3, v3
	v_rcp_f32_e32 v4, v4
	v_rcp_f32_e32 v5, v5
	v_rcp_f32_e32 v6, v6
	v_rcp_f32_e32 v7, v7
	v_rcp_f32_e32 v8, v8
	v_rcp_f32_e32 v9, v9
	v_rcp_f32_e32 v10, v10
	v_rcp_f32_e32 v11, v11
	v_rcp_f32_e32 v12, v12
	v_rcp_f32_e32 v13, v13
	v_rcp_f32_e32 v14, v14
	v_rcp_f32_e32 v15, v15
	v_rcp_f32_e32 v16, v16
	v_rcp_f32_e32 v17, v17
	v_cvt_pk_u8_f32 v22, v2, 0, 0
	v_cvt_pk_u8_f32 v23, v6, 0, 0
	v_cvt_pk_u8_f32 v24, v10, 0, 0
	v_cvt_pk_u8_f32 v25, v14, 0, 0
	v_cvt_pk_u8_f32 v22, v3, 1, v22
	v_cvt_pk_u8_f32 v23, v7, 1, v23
	v_cvt_pk_u8_f32 v24, v11, 1, v24
	v_cvt_pk_u8_f32 v25, v15, 1, v25
	v_cvt_pk_u8_f32 v22, v4, 2, v22
	v_cvt_pk_u8_f32 v23, v8, 2, v23
	v_cvt_pk_u8_f32 v24, v12, 2, v24
	v_cvt_pk_u8_f32 v25, v16, 2, v25
	v_cvt_pk_u8_f32 v22, v5, 3, v22
	v_cvt_pk_u8_f32 v23, v9, 3, v23
	v_cvt_pk_u8_f32 v24, v13, 3, v24
	v_cvt_pk_u8_f32 v25, v17, 3, v25
	global_store_dwordx4 v[26:27], v[22:25], off offset:1024 nt
	v_pk_mul_f32 v[2:3], v[66:67], v[28:29]
	v_pk_mul_f32 v[4:5], v[68:69], v[28:29]
	v_pk_mul_f32 v[6:7], v[62:63], v[28:29]
	v_pk_mul_f32 v[8:9], v[64:65], v[28:29]
	v_pk_mul_f32 v[10:11], v[58:59], v[28:29]
	v_pk_mul_f32 v[12:13], v[60:61], v[28:29]
	v_pk_mul_f32 v[14:15], v[54:55], v[28:29]
	v_pk_mul_f32 v[16:17], v[56:57], v[28:29]
	v_exp_f32_e32 v2, v2
	v_exp_f32_e32 v3, v3
	v_exp_f32_e32 v4, v4
	v_exp_f32_e32 v5, v5
	v_exp_f32_e32 v6, v6
	v_exp_f32_e32 v7, v7
	v_exp_f32_e32 v8, v8
	v_exp_f32_e32 v9, v9
	v_exp_f32_e32 v10, v10
	v_exp_f32_e32 v11, v11
	v_exp_f32_e32 v12, v12
	v_exp_f32_e32 v13, v13
	v_exp_f32_e32 v14, v14
	v_exp_f32_e32 v15, v15
	v_exp_f32_e32 v16, v16
	v_exp_f32_e32 v17, v17
	v_pk_fma_f32 v[2:3], v[2:3], v[216:217], v[216:217] op_sel:[0,1,1] op_sel_hi:[1,1,1] clamp
	v_pk_fma_f32 v[4:5], v[4:5], v[216:217], v[216:217] op_sel:[0,1,1] op_sel_hi:[1,1,1] clamp
	v_pk_fma_f32 v[6:7], v[6:7], v[216:217], v[216:217] op_sel:[0,1,1] op_sel_hi:[1,1,1] clamp
	v_pk_fma_f32 v[8:9], v[8:9], v[216:217], v[216:217] op_sel:[0,1,1] op_sel_hi:[1,1,1] clamp
	v_pk_fma_f32 v[10:11], v[10:11], v[216:217], v[216:217] op_sel:[0,1,1] op_sel_hi:[1,1,1] clamp
	v_pk_fma_f32 v[12:13], v[12:13], v[216:217], v[216:217] op_sel:[0,1,1] op_sel_hi:[1,1,1] clamp
	v_pk_fma_f32 v[14:15], v[14:15], v[216:217], v[216:217] op_sel:[0,1,1] op_sel_hi:[1,1,1] clamp
	v_pk_fma_f32 v[16:17], v[16:17], v[216:217], v[216:217] op_sel:[0,1,1] op_sel_hi:[1,1,1] clamp
	v_rcp_f32_e32 v2, v2
	v_rcp_f32_e32 v3, v3
	v_rcp_f32_e32 v4, v4
	v_rcp_f32_e32 v5, v5
	v_rcp_f32_e32 v6, v6
	v_rcp_f32_e32 v7, v7
	v_rcp_f32_e32 v8, v8
	v_rcp_f32_e32 v9, v9
	v_rcp_f32_e32 v10, v10
	v_rcp_f32_e32 v11, v11
	v_rcp_f32_e32 v12, v12
	v_rcp_f32_e32 v13, v13
	v_rcp_f32_e32 v14, v14
	v_rcp_f32_e32 v15, v15
	v_rcp_f32_e32 v16, v16
	v_rcp_f32_e32 v17, v17
	v_cvt_pk_u8_f32 v18, v2, 0, 0
	v_cvt_pk_u8_f32 v19, v6, 0, 0
	v_cvt_pk_u8_f32 v20, v10, 0, 0
	v_cvt_pk_u8_f32 v21, v14, 0, 0
	v_cvt_pk_u8_f32 v18, v3, 1, v18
	v_cvt_pk_u8_f32 v19, v7, 1, v19
	v_cvt_pk_u8_f32 v20, v11, 1, v20
	v_cvt_pk_u8_f32 v21, v15, 1, v21
	v_cvt_pk_u8_f32 v18, v4, 2, v18
	v_cvt_pk_u8_f32 v19, v8, 2, v19
	v_cvt_pk_u8_f32 v20, v12, 2, v20
	v_cvt_pk_u8_f32 v21, v16, 2, v21
	v_cvt_pk_u8_f32 v18, v5, 3, v18
	v_cvt_pk_u8_f32 v19, v9, 3, v19
	v_cvt_pk_u8_f32 v20, v13, 3, v20
	v_cvt_pk_u8_f32 v21, v17, 3, v21
	global_store_dwordx4 v[26:27], v[18:21], off offset:2048 nt
	v_pk_mul_f32 v[2:3], v[50:51], v[28:29]
	v_pk_mul_f32 v[4:5], v[52:53], v[28:29]
	v_pk_mul_f32 v[6:7], v[46:47], v[28:29]
	v_pk_mul_f32 v[8:9], v[48:49], v[28:29]
	v_pk_mul_f32 v[10:11], v[42:43], v[28:29]
	v_pk_mul_f32 v[12:13], v[44:45], v[28:29]
	v_pk_mul_f32 v[14:15], v[38:39], v[28:29]
	v_pk_mul_f32 v[16:17], v[40:41], v[28:29]
	v_exp_f32_e32 v2, v2
	v_exp_f32_e32 v3, v3
	v_exp_f32_e32 v4, v4
	v_exp_f32_e32 v5, v5
	v_exp_f32_e32 v6, v6
	v_exp_f32_e32 v7, v7
	v_exp_f32_e32 v8, v8
	v_exp_f32_e32 v9, v9
	v_exp_f32_e32 v10, v10
	v_exp_f32_e32 v11, v11
	v_exp_f32_e32 v12, v12
	v_exp_f32_e32 v13, v13
	v_exp_f32_e32 v14, v14
	v_exp_f32_e32 v15, v15
	v_exp_f32_e32 v16, v16
	v_exp_f32_e32 v17, v17
	v_pk_fma_f32 v[2:3], v[2:3], v[216:217], v[216:217] op_sel:[0,1,1] op_sel_hi:[1,1,1] clamp
	v_pk_fma_f32 v[4:5], v[4:5], v[216:217], v[216:217] op_sel:[0,1,1] op_sel_hi:[1,1,1] clamp
	v_pk_fma_f32 v[6:7], v[6:7], v[216:217], v[216:217] op_sel:[0,1,1] op_sel_hi:[1,1,1] clamp
	v_pk_fma_f32 v[8:9], v[8:9], v[216:217], v[216:217] op_sel:[0,1,1] op_sel_hi:[1,1,1] clamp
	v_pk_fma_f32 v[10:11], v[10:11], v[216:217], v[216:217] op_sel:[0,1,1] op_sel_hi:[1,1,1] clamp
	v_pk_fma_f32 v[12:13], v[12:13], v[216:217], v[216:217] op_sel:[0,1,1] op_sel_hi:[1,1,1] clamp
	v_pk_fma_f32 v[14:15], v[14:15], v[216:217], v[216:217] op_sel:[0,1,1] op_sel_hi:[1,1,1] clamp
	v_pk_fma_f32 v[16:17], v[16:17], v[216:217], v[216:217] op_sel:[0,1,1] op_sel_hi:[1,1,1] clamp
	v_rcp_f32_e32 v2, v2
	v_rcp_f32_e32 v3, v3
	v_rcp_f32_e32 v4, v4
	v_rcp_f32_e32 v5, v5
	v_rcp_f32_e32 v6, v6
	v_rcp_f32_e32 v7, v7
	v_rcp_f32_e32 v8, v8
	v_rcp_f32_e32 v9, v9
	v_rcp_f32_e32 v10, v10
	v_rcp_f32_e32 v11, v11
	v_rcp_f32_e32 v12, v12
	v_rcp_f32_e32 v13, v13
	v_rcp_f32_e32 v14, v14
	v_rcp_f32_e32 v15, v15
	v_rcp_f32_e32 v16, v16
	v_rcp_f32_e32 v17, v17
	v_cvt_pk_u8_f32 v22, v2, 0, 0
	v_cvt_pk_u8_f32 v23, v6, 0, 0
	v_cvt_pk_u8_f32 v24, v10, 0, 0
	v_cvt_pk_u8_f32 v25, v14, 0, 0
	v_cvt_pk_u8_f32 v22, v3, 1, v22
	v_cvt_pk_u8_f32 v23, v7, 1, v23
	v_cvt_pk_u8_f32 v24, v11, 1, v24
	v_cvt_pk_u8_f32 v25, v15, 1, v25
	v_cvt_pk_u8_f32 v22, v4, 2, v22
	v_cvt_pk_u8_f32 v23, v8, 2, v23
	v_cvt_pk_u8_f32 v24, v12, 2, v24
	v_cvt_pk_u8_f32 v25, v16, 2, v25
	v_cvt_pk_u8_f32 v22, v5, 3, v22
	v_cvt_pk_u8_f32 v23, v9, 3, v23
	v_cvt_pk_u8_f32 v24, v13, 3, v24
	v_cvt_pk_u8_f32 v25, v17, 3, v25
	global_store_dwordx4 v[26:27], v[22:25], off offset:3072 nt
	s_andn2_b64 vcc, exec, s[30:31]
	s_mov_b64 s[8:9], -1
	s_cbranch_vccnz .LBB0_473
	s_branch .LBB0_539

.LBB0_762:
	s_andn2_b64 vcc, exec, s[8:9]
	s_cbranch_vccnz .LBB0_804
	s_bfe_u32 s0, s95, 0x10005
	s_ashr_i32 s10, s95, 6
	s_and_b32 s78, s95, 31
	s_lshl_b32 s6, s0, 2
	v_readlane_b32 s7, v254, 34
	s_or_b32 s8, s6, s7
	s_lshl_b32 s79, s10, 12
	s_lshl_b32 s6, s78, 7
	s_or_b32 s11, s6, s79
	v_readlane_b32 s13, v254, 38
	s_add_i32 s82, s11, s13
	s_lshl_b32 s57, s8, 6
	s_lshl_b32 s6, s8, 7
	s_add_u32 s6, s70, s6
	s_addc_u32 s7, s71, 0
	v_and_b32_e32 v32, 48, v207
	s_lshl_b32 s5, s5, 3
	v_and_b32_e32 v201, 15, v206
	v_lshl_add_u64 v[2:3], s[6:7], 0, v[32:33]
	s_or_b32 s6, s8, s5
	v_or_b32_e32 v0, s82, v201
	s_ashr_i32 s7, s6, 31
	v_ashrrev_i32_e32 v1, 31, v0
	s_lshl_b64 s[6:7], s[6:7], 2
	v_lshlrev_b64 v[4:5], 13, v[0:1]
	s_add_u32 s6, s36, s6
	s_addc_u32 s7, s37, s7
	v_lshl_add_u64 v[4:5], v[2:3], 0, v[4:5]
	global_load_dword v6, v33, s[6:7]
	global_load_dwordx4 v[72:75], v[4:5], off
	global_load_dwordx4 v[76:79], v[4:5], off offset:64
	v_or_b32_e32 v4, 16, v0
	v_ashrrev_i32_e32 v5, 31, v4
	s_add_i32 s5, s78, -1
	v_lshlrev_b64 v[4:5], 13, v[4:5]
	s_cmp_gt_u32 s5, 31
	v_lshl_add_u64 v[4:5], v[2:3], 0, v[4:5]
	s_cselect_b64 s[6:7], -1, 0
	s_lshl_b32 s8, s5, 7
	global_load_dwordx4 v[84:87], v[4:5], off
	global_load_dwordx4 v[88:91], v[4:5], off offset:64
	v_or_b32_e32 v4, 32, v0
	v_or_b32_e32 v0, 48, v0
	s_add_i32 s12, s8, s79
	v_ashrrev_i32_e32 v5, 31, v4
	v_ashrrev_i32_e32 v1, 31, v0
	s_cmp_lt_u32 s5, 32
	v_lshlrev_b64 v[4:5], 13, v[4:5]
	v_lshlrev_b64 v[0:1], 13, v[0:1]
	s_cselect_b64 s[8:9], -1, 0
	v_lshl_add_u64 v[4:5], v[2:3], 0, v[4:5]
	v_lshl_add_u64 v[0:1], v[2:3], 0, v[0:1]
	v_cndmask_b32_e64 v3, 0, 1, s[8:9]
	s_and_b64 s[8:9], s[8:9], exec
	global_load_dwordx4 v[100:103], v[4:5], off
	global_load_dwordx4 v[104:107], v[4:5], off offset:64
	global_load_dwordx4 v[108:111], v[0:1], off
	global_load_dwordx4 v[112:115], v[0:1], off offset:64
	v_ashrrev_i32_e32 v205, 3, v206
	s_cselect_b32 s5, s12, s11
	s_lshl_b32 s0, s0, 7
	v_lshlrev_b32_e32 v1, 3, v206
	v_add_u32_e32 v0, s5, v205
	s_add_u32 s8, s70, s0
	v_and_b32_e32 v2, 56, v1
	s_addc_u32 s9, s71, 0
	v_lshlrev_b32_e32 v32, 1, v2
	v_ashrrev_i32_e32 v1, 31, v0
	v_lshl_add_u64 v[202:203], s[8:9], 0, v[32:33]
	v_lshlrev_b64 v[0:1], 13, v[0:1]
	v_lshl_add_u64 v[0:1], v[202:203], 0, v[0:1]
	s_mov_b64 s[8:9], 0x80000
	global_load_dwordx4 v[120:123], v[0:1], off offset:1024
	global_load_dwordx4 v[124:127], v[0:1], off offset:1280
	v_lshl_add_u64 v[0:1], v[0:1], 0, s[8:9]
	global_load_dwordx4 v[128:131], v[0:1], off offset:1024
	global_load_dwordx4 v[132:135], v[0:1], off offset:1280
	v_lshrrev_b32_e32 v0, 4, v207
	s_movk_i32 s0, 0x48
	v_and_b32_e32 v5, -8, v206
	v_lshlrev_b32_e32 v204, 3, v0
	v_lshlrev_b32_e32 v7, 2, v0
	v_mad_u64_u32 v[0:1], s[8:9], v205, s0, v[2:3]
	v_lshlrev_b32_e32 v209, 1, v0
	v_cndmask_b32_e64 v1, 0, 1, s[6:7]
	v_add_lshl_u32 v211, v0, v5, 1
	v_add_u32_e32 v0, 0x1200, v0
	v_readfirstlane_b32 s16, v1
	v_lshlrev_b32_e32 v212, 1, v0
	v_add_u32_e32 v0, v5, v0
	v_mov_b32_e32 v1, 0x400
	v_lshl_add_u32 v213, v0, 1, v1
	v_add_u32_e32 v0, s13, v201
	v_bfe_u32 v4, v206, 2, 2
	v_sub_u32_e32 v214, v0, v7
	v_and_b32_e32 v0, 3, v206
	v_readlane_b32 s6, v254, 15
	v_mov_b32_e32 v37, v36
	v_mov_b32_e32 v38, v36
	v_mov_b32_e32 v39, v36
	v_mov_b32_e32 v32, v33
	v_mov_b32_e32 v34, v33
	v_mov_b32_e32 v35, v33
	v_readfirstlane_b32 s0, v3
	s_lshl_b32 s5, s10, 8
	v_lshl_add_u32 v215, v0, 3, s6
	v_or_b32_e32 v243, v4, v7
	v_mov_b64_e32 v[0:1], v[32:33]
	v_mov_b64_e32 v[20:21], v[32:33]
	v_mov_b64_e32 v[50:51], v[34:35]
	v_mov_b64_e32 v[70:71], v[34:35]
	v_mov_b64_e32 v[8:9], v[32:33]
	v_mov_b64_e32 v[42:43], v[34:35]
	s_waitcnt vmcnt(12)
	v_mul_f32_e32 v210, 0x3fb8aa3b, v6
	v_mov_b64_e32 v[62:63], v[34:35]
	v_mov_b64_e32 v[98:99], v[34:35]
	v_mov_b64_e32 v[16:17], v[36:37]
	v_mov_b64_e32 v[46:47], v[38:39]
	v_mov_b64_e32 v[66:67], v[38:39]
	v_mov_b64_e32 v[118:119], v[38:39]
	v_mov_b64_e32 v[94:95], v[34:35]
	v_mov_b64_e32 v[58:59], v[34:35]
	v_mov_b64_e32 v[28:29], v[32:33]
	v_mov_b64_e32 v[12:13], v[32:33]
	v_mov_b64_e32 v[82:83], v[34:35]
	v_mov_b64_e32 v[54:55], v[34:35]
	v_mov_b64_e32 v[24:25], v[32:33]
	v_mov_b64_e32 v[4:5], v[32:33]
	v_and_b32_e32 v208, 48, v206
	s_addk_i32 s5, 0x3e80
	s_mov_b32 s83, s78
	s_mov_b32 s92, s78
	s_mov_b32 s95, s78
	s_mov_b32 s96, s78
	s_mov_b32 s97, s78
	s_mov_b32 s64, s78
	s_mov_b32 s81, s78
	s_mov_b32 s90, 0
	v_mov_b64_e32 v[2:3], v[34:35]
	v_mov_b64_e32 v[22:23], v[34:35]
	v_mov_b64_e32 v[48:49], v[32:33]
	v_mov_b64_e32 v[68:69], v[32:33]
	v_mov_b64_e32 v[10:11], v[34:35]
	v_mov_b64_e32 v[40:41], v[32:33]
	v_mov_b64_e32 v[60:61], v[32:33]
	v_mov_b64_e32 v[96:97], v[32:33]
	v_mov_b32_e32 v244, v210
	v_mov_b32_e32 v245, v210
	v_mov_b32_e32 v246, v210
	v_xor_b32_e32 v228, 0x80000000, v210
	v_mov_b32_e32 v229, v228
	v_mov_b32_e32 v230, v228
	v_mov_b32_e32 v231, v228
	v_mov_b32_e32 v232, v228
	v_mov_b32_e32 v233, v228
	v_mov_b32_e32 v234, v228
	v_mov_b32_e32 v235, v228
	v_mov_b32_e32 v248, v228
	v_mov_b32_e32 v249, v228
	v_mov_b32_e32 v250, v228
	v_mov_b32_e32 v251, v228
	v_mov_b32_e32 v220, v228
	v_mov_b32_e32 v221, v228
	v_mov_b32_e32 v222, v228
	v_mov_b32_e32 v223, v228
	v_mov_b64_e32 v[18:19], v[38:39]
	v_mov_b64_e32 v[44:45], v[36:37]
	v_mov_b64_e32 v[64:65], v[36:37]
	v_mov_b64_e32 v[116:117], v[36:37]
	v_mov_b64_e32 v[92:93], v[32:33]
	v_mov_b64_e32 v[56:57], v[32:33]
	v_mov_b64_e32 v[30:31], v[34:35]
	v_mov_b64_e32 v[14:15], v[34:35]
	v_mov_b64_e32 v[80:81], v[32:33]
	v_mov_b64_e32 v[52:53], v[32:33]
	v_mov_b64_e32 v[26:27], v[34:35]
	v_mov_b64_e32 v[6:7], v[34:35]
	s_barrier

.LBB0_787:
	s_cmp_eq_u32 s0, 1
	s_cselect_b64 s[6:7], -1, 0
	s_and_b64 s[8:9], s[46:47], s[6:7]
	s_and_b64 s[8:9], s[8:9], exec
	s_cselect_b32 s53, 2, 0
	s_cmp_eq_u32 s0, 2
	s_cselect_b64 s[8:9], -1, 0
	s_and_b64 s[8:9], s[88:89], s[8:9]
	s_and_b64 s[8:9], s[8:9], exec
	s_cselect_b32 s52, 2, 4
	s_cmp_ge_u32 s53, s52
	s_cbranch_scc1 .LBB0_801
	s_lshl_b32 s8, s53, 5
	v_add_u32_e32 v32, s54, v208
	v_or_b32_e32 v34, s8, v201
	v_mad_u32_u24 v34, v34, s3, v32
	ds_read_b128 v[144:147], v34
	ds_read_b128 v[148:151], v34 offset:64
	ds_read_b128 v[140:143], v34 offset:2304
	ds_read_b128 v[136:139], v34 offset:2368
	s_cmp_lg_u32 s0, 0
	s_cselect_b64 s[86:87], -1, 0
	s_and_b64 s[6:7], s[6:7], exec
	s_cselect_b32 s54, 1, -1
	v_or_b32_e32 v35, s8, v243
	s_lshl_b32 s84, s54, 4
	s_lshl_b32 s73, s54, 5
	v_subrev_u32_e32 v34, s8, v214
	v_mul_u32_u24_e32 v35, 0xa0, v35
	s_lshl_b32 s55, s54, 1
	s_sub_i32 s85, 0, s84
	s_sub_i32 s0, 0, s73
	v_mul_lo_u32 v34, s54, v34
	v_add3_u32 v35, s61, v35, v215
	v_add_u32_e32 v35, 0xfffff5a0, v35
	s_branch .LBB0_790

.LBB0_790:
	s_waitcnt lgkmcnt(3)
	v_mfma_f32_16x16x32_bf16 v[152:155], v[144:147], v[72:75], v[228:231]
	s_waitcnt lgkmcnt(2)
	v_mfma_f32_16x16x32_bf16 v[192:195], v[148:151], v[76:79], v[152:155]
	v_mfma_f32_16x16x32_bf16 v[152:155], v[144:147], v[84:87], v[232:235]
	v_mfma_f32_16x16x32_bf16 v[180:183], v[148:151], v[88:91], v[152:155]
	s_mov_b32 s6, s53
	s_add_i32 s53, s53, 1
	s_cmp_ge_u32 s53, s52
	v_mfma_f32_16x16x32_bf16 v[152:155], v[144:147], v[100:103], v[248:251]
	s_cselect_b64 s[34:35], -1, 0
	s_cmp_lt_u32 s53, s52
	s_cselect_b32 s6, s53, s6
	v_mfma_f32_16x16x32_bf16 v[144:147], v[144:147], v[108:111], v[220:223]
	v_lshl_or_b32 v37, s6, 5, v201
	v_mad_u64_u32 v[38:39], s[6:7], v37, s3, v[32:33]
	v_mfma_f32_16x16x32_bf16 v[156:159], v[148:151], v[104:107], v[152:155]
	v_mfma_f32_16x16x32_bf16 v[152:155], v[148:151], v[112:115], v[144:147]
	s_waitcnt lgkmcnt(1)
	v_mfma_f32_16x16x32_bf16 v[144:147], v[140:143], v[72:75], v[228:231]
	s_waitcnt lgkmcnt(0)
	v_mfma_f32_16x16x32_bf16 v[196:199], v[136:139], v[76:79], v[144:147]
	s_nop 0
	v_mfma_f32_16x16x32_bf16 v[144:147], v[140:143], v[84:87], v[232:235]
	v_mfma_f32_16x16x32_bf16 v[188:191], v[136:139], v[88:91], v[144:147]
	v_mfma_f32_16x16x32_bf16 v[144:147], v[140:143], v[100:103], v[248:251]
	v_mfma_f32_16x16x32_bf16 v[140:143], v[140:143], v[108:111], v[220:223]
	v_mfma_f32_16x16x32_bf16 v[184:187], v[136:139], v[104:107], v[144:147]
	s_nop 5
	ds_read_b128 v[144:147], v38
	ds_read_b128 v[148:151], v38 offset:64
	v_mfma_f32_16x16x32_bf16 v[172:175], v[136:139], v[112:115], v[140:143]
	s_nop 2
	ds_read_b128 v[140:143], v38 offset:2304
	ds_read_b128 v[136:139], v38 offset:2368
	ds_read_b64_tr_b16 v[168:169], v35
	ds_read_b64_tr_b16 v[170:171], v35 offset:2560
	ds_read_b64_tr_b16 v[160:161], v35 offset:32
	ds_read_b64_tr_b16 v[162:163], v35 offset:2592
	ds_read_b64_tr_b16 v[176:177], v35 offset:64
	ds_read_b64_tr_b16 v[178:179], v35 offset:2624
	ds_read_b64_tr_b16 v[164:165], v35 offset:96
	ds_read_b64_tr_b16 v[166:167], v35 offset:2656
	s_andn2_b64 vcc, exec, s[86:87]
	s_cbranch_vccnz .LBB0_792
	s_mul_i32 s30, s54, 0xffffffd0
	v_mov_b32_e32 v38, s4
	v_cmp_lt_i32_e64 s[30:31], s30, v34
	s_mul_i32 s10, s54, 3
	s_mul_i32 s16, s54, -15
	v_cndmask_b32_e64 v152, v152, v38, s[30:31]
	s_mul_i32 s30, s54, 0xffffffd1
	v_cmp_ge_i32_e64 s[30:31], s30, v34
	s_mul_i32 s18, s54, -14
	s_mul_i32 s20, s54, -13
	v_cndmask_b32_e64 v153, v241, v153, s[30:31]
	s_mul_i32 s30, s54, 0xffffffd2
	v_cmp_ge_i32_e64 s[30:31], s30, v34
	s_mul_i32 s24, s54, 0xffffffe1
	s_mul_i32 s26, s54, 0xffffffe2
	v_cndmask_b32_e64 v154, v241, v154, s[30:31]
	s_mul_i32 s30, s54, 0xffffffd3
	v_cmp_ge_i32_e64 s[30:31], s30, v34
	s_mul_i32 s28, s54, 0xffffffe3
	v_cmp_lt_i32_e32 vcc, 0, v34
	v_cndmask_b32_e64 v155, v241, v155, s[30:31]
	v_cmp_lt_i32_e64 s[30:31], s84, v34
	v_cmp_lt_i32_e64 s[6:7], s54, v34
	v_cmp_lt_i32_e64 s[8:9], s55, v34
	v_cndmask_b32_e64 v196, v196, v38, s[30:31]
	s_mul_i32 s30, s54, 17
	v_cmp_ge_i32_e64 s[30:31], s30, v34
	v_cmp_lt_i32_e64 s[10:11], s10, v34
	v_cmp_lt_i32_e64 s[12:13], s85, v34
	v_cndmask_b32_e64 v197, v241, v197, s[30:31]
	s_mul_i32 s30, s54, 18
	v_cmp_ge_i32_e64 s[30:31], s30, v34
	v_cmp_lt_i32_e64 s[16:17], s16, v34
	v_cmp_lt_i32_e64 s[18:19], s18, v34
	v_cndmask_b32_e64 v198, v241, v198, s[30:31]
	s_mul_i32 s30, s54, 19
	v_cmp_lt_i32_e64 s[20:21], s20, v34
	v_cmp_lt_i32_e64 s[22:23], s0, v34
	v_cmp_lt_i32_e64 s[24:25], s24, v34
	v_cmp_lt_i32_e64 s[26:27], s26, v34
	v_cmp_lt_i32_e64 s[28:29], s28, v34
	v_cmp_ge_i32_e64 s[30:31], s30, v34
	v_cndmask_b32_e32 v192, v192, v38, vcc
	v_cndmask_b32_e64 v193, v193, v241, s[6:7]
	v_cndmask_b32_e64 v194, v194, v241, s[8:9]
	v_cndmask_b32_e64 v195, v195, v241, s[10:11]
	v_cndmask_b32_e64 v180, v180, v38, s[12:13]
	v_cndmask_b32_e64 v181, v181, v241, s[16:17]
	v_cndmask_b32_e64 v182, v182, v241, s[18:19]
	v_cndmask_b32_e64 v183, v183, v241, s[20:21]
	v_cndmask_b32_e64 v156, v156, v38, s[22:23]
	v_cndmask_b32_e64 v157, v157, v241, s[24:25]
	v_cndmask_b32_e64 v158, v158, v241, s[26:27]
	v_cndmask_b32_e64 v159, v159, v241, s[28:29]
	v_cndmask_b32_e64 v199, v241, v199, s[30:31]
	v_cndmask_b32_e32 v188, v188, v38, vcc
	v_cndmask_b32_e64 v189, v189, v241, s[6:7]
	v_cndmask_b32_e64 v190, v190, v241, s[8:9]
	v_cndmask_b32_e64 v191, v191, v241, s[10:11]
	v_cndmask_b32_e64 v184, v184, v38, s[12:13]
	v_cndmask_b32_e64 v185, v185, v241, s[16:17]
	v_cndmask_b32_e64 v186, v186, v241, s[18:19]
	v_cndmask_b32_e64 v187, v187, v241, s[20:21]
	v_cndmask_b32_e64 v172, v172, v38, s[22:23]
	v_cndmask_b32_e64 v173, v173, v241, s[24:25]
	v_cndmask_b32_e64 v174, v174, v241, s[26:27]
	v_cndmask_b32_e64 v175, v175, v241, s[28:29]
.LBB0_792:
	v_max_i32_e32 v37, v192, v193
	v_max3_i32 v37, v37, v194, v195
	v_max3_i32 v37, v37, v196, v197
	v_max3_i32 v247, v37, v198, v199
	v_max_i32_e32 v37, v180, v181
	v_max3_i32 v37, v37, v182, v183
	v_max3_i32 v37, v37, v188, v189
	v_max3_i32 v39, v37, v190, v191
	v_max_i32_e32 v37, v156, v157
	v_max3_i32 v37, v37, v158, v159
	v_max3_i32 v37, v37, v184, v185
	v_max3_i32 v38, v37, v186, v187
	v_max_i32_e32 v37, v152, v153
	v_max3_i32 v37, v37, v154, v155
	v_max3_i32 v37, v37, v172, v173
	v_max3_i32 v37, v37, v174, v175
	v_max_i32_e32 v218, v38, v37
	v_max3_i32 v218, v247, v39, v218
	v_cmp_lt_i32_e32 vcc, s45, v218
	s_cbranch_vccz .LBB0_789
	v_cmp_lt_i32_e32 vcc, s45, v247
	s_cbranch_vccz .LBB0_795
	v_max_f32_e32 v218, v193, v193
	v_max_f32_e32 v219, v192, v192
	v_max_f32_e32 v218, v219, v218
	v_max_f32_e32 v219, v195, v195
	v_max_f32_e32 v236, v194, v194
	v_max_f32_e32 v219, v236, v219
	v_max_f32_e32 v236, v199, v199
	v_max_f32_e32 v237, v198, v198
	v_max_f32_e32 v236, v237, v236
	v_max3_f32 v236, v196, v197, v236
	v_max3_f32 v218, v218, v219, v236
	v_mov_b32_e32 v219, v218
	s_nop 1
	v_permlane16_swap_b32 v218, v219
	s_nop 1
	s_nop 0
	v_max_f32_e32 v219, v219, v219
	v_max_f32_e32 v218, v218, v218
	v_max_f32_e32 v218, v218, v219
	v_mov_b32_e32 v219, v218
	s_nop 1
	v_permlane32_swap_b32 v218, v219
	s_nop 1
	s_nop 0
	v_max3_f32 v219, v218, v219, 0
	v_exp_f32_e64 v218, -v219
	v_add_f32_e32 v246, v246, v219
	v_sub_f32_e32 v228, v228, v219
	v_sub_f32_e32 v229, v229, v219
	v_sub_f32_e32 v230, v230, v219
	v_sub_f32_e32 v231, v231, v219
	v_sub_f32_e32 v195, v195, v219
	v_sub_f32_e32 v194, v194, v219
	v_pk_mul_f32 v[118:119], v[118:119], v[218:219] op_sel_hi:[1,0]
	v_pk_mul_f32 v[116:117], v[116:117], v[218:219] op_sel_hi:[1,0]
	v_sub_f32_e32 v193, v193, v219
	v_sub_f32_e32 v192, v192, v219
	v_sub_f32_e32 v199, v199, v219
	v_sub_f32_e32 v198, v198, v219
	v_sub_f32_e32 v197, v197, v219
	v_sub_f32_e32 v196, v196, v219
	v_pk_mul_f32 v[98:99], v[98:99], v[218:219] op_sel_hi:[1,0]
	v_pk_mul_f32 v[96:97], v[96:97], v[218:219] op_sel_hi:[1,0]
	v_pk_mul_f32 v[70:71], v[70:71], v[218:219] op_sel_hi:[1,0]
	v_pk_mul_f32 v[68:69], v[68:69], v[218:219] op_sel_hi:[1,0]
	v_pk_mul_f32 v[94:95], v[94:95], v[218:219] op_sel_hi:[1,0]
	v_pk_mul_f32 v[92:93], v[92:93], v[218:219] op_sel_hi:[1,0]
	v_pk_mul_f32 v[82:83], v[82:83], v[218:219] op_sel_hi:[1,0]
	v_pk_mul_f32 v[80:81], v[80:81], v[218:219] op_sel_hi:[1,0]
.LBB0_795:
	v_cmp_lt_i32_e32 vcc, s45, v39
	s_cbranch_vccz .LBB0_797
	v_max_f32_e32 v39, v181, v181
	v_max_f32_e32 v218, v180, v180
	v_max_f32_e32 v39, v218, v39
	v_max_f32_e32 v218, v183, v183
	v_max_f32_e32 v219, v182, v182
	v_max_f32_e32 v218, v219, v218
	v_max_f32_e32 v219, v191, v191
	v_max_f32_e32 v236, v190, v190
	v_max_f32_e32 v219, v236, v219
	v_max3_f32 v219, v188, v189, v219
	v_max3_f32 v39, v39, v218, v219
	v_mov_b32_e32 v218, v39
	s_nop 1
	v_permlane16_swap_b32 v39, v218
	s_nop 1
	s_nop 0
	v_max_f32_e32 v218, v218, v218
	v_max_f32_e32 v39, v39, v39
	v_max_f32_e32 v39, v39, v218
	v_mov_b32_e32 v218, v39
	s_nop 1
	v_permlane32_swap_b32 v39, v218
	s_nop 1
	s_nop 0
	v_max3_f32 v39, v39, v218, 0
	v_exp_f32_e64 v218, -v39
	v_add_f32_e32 v245, v245, v39
	v_sub_f32_e32 v232, v232, v39
	v_sub_f32_e32 v233, v233, v39
	v_sub_f32_e32 v234, v234, v39
	v_sub_f32_e32 v235, v235, v39
	v_sub_f32_e32 v183, v183, v39
	v_sub_f32_e32 v182, v182, v39
	v_pk_mul_f32 v[66:67], v[66:67], v[218:219] op_sel_hi:[1,0]
	v_pk_mul_f32 v[64:65], v[64:65], v[218:219] op_sel_hi:[1,0]
	v_sub_f32_e32 v181, v181, v39
	v_sub_f32_e32 v180, v180, v39
	v_sub_f32_e32 v191, v191, v39
	v_sub_f32_e32 v190, v190, v39
	v_sub_f32_e32 v189, v189, v39
	v_sub_f32_e32 v188, v188, v39
	v_pk_mul_f32 v[62:63], v[62:63], v[218:219] op_sel_hi:[1,0]
	v_pk_mul_f32 v[60:61], v[60:61], v[218:219] op_sel_hi:[1,0]
	v_pk_mul_f32 v[50:51], v[50:51], v[218:219] op_sel_hi:[1,0]
	v_pk_mul_f32 v[48:49], v[48:49], v[218:219] op_sel_hi:[1,0]
	v_pk_mul_f32 v[58:59], v[58:59], v[218:219] op_sel_hi:[1,0]
	v_pk_mul_f32 v[56:57], v[56:57], v[218:219] op_sel_hi:[1,0]
	v_pk_mul_f32 v[54:55], v[54:55], v[218:219] op_sel_hi:[1,0]
	v_pk_mul_f32 v[52:53], v[52:53], v[218:219] op_sel_hi:[1,0]
.LBB0_797:
	v_cmp_lt_i32_e32 vcc, s45, v38
	s_cbranch_vccz .LBB0_799
	v_max_f32_e32 v38, v157, v157
	v_max_f32_e32 v39, v156, v156
	v_max_f32_e32 v38, v39, v38
	v_max_f32_e32 v39, v159, v159
	v_max_f32_e32 v218, v158, v158
	v_max_f32_e32 v39, v218, v39
	v_max_f32_e32 v218, v187, v187
	v_max_f32_e32 v219, v186, v186
	v_max_f32_e32 v218, v219, v218
	v_max3_f32 v218, v184, v185, v218
	v_max3_f32 v38, v38, v39, v218
	v_mov_b32_e32 v39, v38
	s_nop 1
	v_permlane16_swap_b32 v38, v39
	s_nop 1
	s_nop 0
	v_max_f32_e32 v39, v39, v39
	v_max_f32_e32 v38, v38, v38
	v_max_f32_e32 v38, v38, v39
	v_mov_b32_e32 v39, v38
	s_nop 1
	v_permlane32_swap_b32 v38, v39
	s_nop 1
	s_nop 0
	v_max3_f32 v39, v38, v39, 0
	v_exp_f32_e64 v38, -v39
	v_add_f32_e32 v244, v244, v39
	v_sub_f32_e32 v248, v248, v39
	v_sub_f32_e32 v249, v249, v39
	v_sub_f32_e32 v250, v250, v39
	v_sub_f32_e32 v251, v251, v39
	v_sub_f32_e32 v159, v159, v39
	v_sub_f32_e32 v158, v158, v39
	v_pk_mul_f32 v[46:47], v[46:47], v[38:39] op_sel_hi:[1,0]
	v_pk_mul_f32 v[44:45], v[44:45], v[38:39] op_sel_hi:[1,0]
	v_sub_f32_e32 v157, v157, v39
	v_sub_f32_e32 v156, v156, v39
	v_sub_f32_e32 v187, v187, v39
	v_sub_f32_e32 v186, v186, v39
	v_sub_f32_e32 v185, v185, v39
	v_sub_f32_e32 v184, v184, v39
	v_pk_mul_f32 v[42:43], v[42:43], v[38:39] op_sel_hi:[1,0]
	v_pk_mul_f32 v[40:41], v[40:41], v[38:39] op_sel_hi:[1,0]
	v_pk_mul_f32 v[22:23], v[22:23], v[38:39] op_sel_hi:[1,0]
	v_pk_mul_f32 v[20:21], v[20:21], v[38:39] op_sel_hi:[1,0]
	v_pk_mul_f32 v[30:31], v[30:31], v[38:39] op_sel_hi:[1,0]
	v_pk_mul_f32 v[28:29], v[28:29], v[38:39] op_sel_hi:[1,0]
	v_pk_mul_f32 v[26:27], v[26:27], v[38:39] op_sel_hi:[1,0]
	v_pk_mul_f32 v[24:25], v[24:25], v[38:39] op_sel_hi:[1,0]
.LBB0_799:
	v_cmp_lt_i32_e32 vcc, s45, v37
	s_cbranch_vccz .LBB0_789
	v_max_f32_e32 v37, v153, v153
	v_max_f32_e32 v38, v152, v152
	v_max_f32_e32 v37, v38, v37
	v_max_f32_e32 v38, v155, v155
	v_max_f32_e32 v39, v154, v154
	v_max_f32_e32 v38, v39, v38
	v_max_f32_e32 v39, v175, v175
	v_max_f32_e32 v218, v174, v174
	v_max_f32_e32 v39, v218, v39
	v_max3_f32 v39, v172, v173, v39
	v_max3_f32 v37, v37, v38, v39
	v_mov_b32_e32 v38, v37
	s_nop 1
	v_permlane16_swap_b32 v37, v38
	s_nop 1
	s_nop 0
	v_max_f32_e32 v38, v38, v38
	v_max_f32_e32 v37, v37, v37
	v_max_f32_e32 v37, v37, v38
	v_mov_b32_e32 v38, v37
	s_nop 1
	v_permlane32_swap_b32 v37, v38
	s_nop 1
	s_nop 0
	v_max3_f32 v37, v37, v38, 0
	v_exp_f32_e64 v38, -v37
	v_add_f32_e32 v210, v210, v37
	v_sub_f32_e32 v220, v220, v37
	v_sub_f32_e32 v221, v221, v37
	v_sub_f32_e32 v222, v222, v37
	v_sub_f32_e32 v223, v223, v37
	v_sub_f32_e32 v155, v155, v37
	v_sub_f32_e32 v154, v154, v37
	v_pk_mul_f32 v[18:19], v[18:19], v[38:39] op_sel_hi:[1,0]
	v_pk_mul_f32 v[16:17], v[16:17], v[38:39] op_sel_hi:[1,0]
	v_sub_f32_e32 v153, v153, v37
	v_sub_f32_e32 v152, v152, v37
	v_sub_f32_e32 v175, v175, v37
	v_sub_f32_e32 v174, v174, v37
	v_sub_f32_e32 v173, v173, v37
	v_sub_f32_e32 v172, v172, v37
	v_pk_mul_f32 v[10:11], v[10:11], v[38:39] op_sel_hi:[1,0]
	v_pk_mul_f32 v[8:9], v[8:9], v[38:39] op_sel_hi:[1,0]
	v_pk_mul_f32 v[2:3], v[2:3], v[38:39] op_sel_hi:[1,0]
	v_pk_mul_f32 v[0:1], v[0:1], v[38:39] op_sel_hi:[1,0]
	v_pk_mul_f32 v[14:15], v[14:15], v[38:39] op_sel_hi:[1,0]
	v_pk_mul_f32 v[12:13], v[12:13], v[38:39] op_sel_hi:[1,0]
	v_pk_mul_f32 v[6:7], v[6:7], v[38:39] op_sel_hi:[1,0]
	v_pk_mul_f32 v[4:5], v[4:5], v[38:39] op_sel_hi:[1,0]
	s_branch .LBB0_789
